# LN split-chunk assembly: residual + 8 partial loads back to back with counted waits (one round trip instead of two), entry drain kept
# baseline (speedup 1.0000x reference)
; __device__ __forceinline__ void ln_load_row(const Params& p, const float* src, int which, int r, int lane, f32x4 (&x)[8]) {
;     ...
;   for (int k = 0; k < 8; ++k) {
;     const int wg = gid * 64 + k * gsz + (pm - fm), off = wg % 36, xcd = wg / 36;
;     if (off >= 32) {
;       const int j = (off - 32) * 8 + xcd;
;       f32x4 v = *(const f32x4*)(rs + 256 * k + 4 * lane) * ALPHA;
;       const float* pp = part + (size_t)j * 8 * 65536 + (r & 255) * 256 + 4 * lane;
;       f32x4 t[8];
; #pragma unroll
;       for (int q = 0; q < 8; ++q) t[q] = *(const f32x4*)(pp + (size_t)q * 65536);
; #pragma unroll
;       for (int q = 0; q < 8; ++q) v += t[q];
;       x[k] = v;
;     } else x[k] = *(const f32x4*)(s + 256 * k + 4 * lane);
.LBB0_94:
	s_or_saveexec_b64 s[36:37], s[36:37]
	v_add_u32_e32 v64, 0xffffe000, v66
	v_lshlrev_b64 v[36:37], 13, v[64:65]
	v_lshl_add_u64 v[36:37], s[6:7], 0, v[36:37]
	v_cndmask_b32_e32 v37, v37, v101, vcc
	v_cndmask_b32_e32 v36, v36, v100, vcc
	v_lshlrev_b32_e32 v64, 2, v68
	v_lshl_add_u64 v[114:115], v[36:37], 0, v[64:65]
	v_and_b32_e32 v36, 0xff00, v129
	v_lshlrev_b32_e32 v36, 2, v36
	v_mov_b32_e32 v37, v65
	v_lshl_add_u64 v[116:117], v[92:93], 0, v[36:37]
	s_xor_b64 exec, exec, s[36:37]
	s_cbranch_execz .LBB0_96
	s_waitcnt vmcnt(0)
	v_lshlrev_b32_e32 v24, 3, v35
	s_movk_i32 s29, 0xff00
	v_add3_u32 v34, v34, v24, s29
	v_ashrrev_i32_e32 v35, 31, v34
	v_lshlrev_b64 v[34:35], 21, v[34:35]
	v_lshl_add_u64 v[38:39], v[116:117], 0, v[34:35]
	v_add_co_u32_e32 v44, vcc, 0x40000, v38
	global_load_dwordx4 v[24:27], v[114:115], off
	s_nop 0
	v_addc_co_u32_e32 v45, vcc, 0, v39, vcc
	v_add_co_u32_e32 v48, vcc, 0x80000, v38
	global_load_dwordx4 v[34:37], v[38:39], off
	s_nop 0
	global_load_dwordx4 v[44:47], v[44:45], off
	v_addc_co_u32_e32 v49, vcc, 0, v39, vcc
	v_add_co_u32_e32 v52, vcc, 0xc0000, v38
	s_nop 1
	v_addc_co_u32_e32 v53, vcc, 0, v39, vcc
	v_add_co_u32_e32 v56, vcc, 0x100000, v38
	global_load_dwordx4 v[48:51], v[48:49], off
	s_nop 0
	global_load_dwordx4 v[52:55], v[52:53], off
	v_addc_co_u32_e32 v57, vcc, 0, v39, vcc
	v_add_co_u32_e32 v60, vcc, 0x140000, v38
	s_nop 0
	s_nop 1
	v_addc_co_u32_e32 v61, vcc, 0, v39, vcc
	v_add_co_u32_e32 v118, vcc, 0x180000, v38
	global_load_dwordx4 v[56:59], v[56:57], off
	s_nop 0
	global_load_dwordx4 v[60:63], v[60:61], off
	v_addc_co_u32_e32 v119, vcc, 0, v39, vcc
	v_add_co_u32_e32 v38, vcc, 0x1c0000, v38
	global_load_dwordx4 v[118:121], v[118:119], off
	s_nop 0
	v_addc_co_u32_e32 v39, vcc, 0, v39, vcc
	global_load_dwordx4 v[130:133], v[38:39], off
	s_waitcnt vmcnt(7)
	v_pk_fma_f32 v[26:27], v[26:27], s[2:3], v[36:37] op_sel_hi:[1,0,1]
	v_pk_fma_f32 v[24:25], v[24:25], s[2:3], v[34:35] op_sel_hi:[1,0,1]
	s_waitcnt vmcnt(6)
	v_pk_add_f32 v[26:27], v[26:27], v[46:47]
	v_pk_add_f32 v[24:25], v[24:25], v[44:45]
	s_waitcnt vmcnt(5)
	v_pk_add_f32 v[26:27], v[26:27], v[50:51]
	v_pk_add_f32 v[24:25], v[24:25], v[48:49]
	s_waitcnt vmcnt(4)
	v_pk_add_f32 v[26:27], v[26:27], v[54:55]
	v_pk_add_f32 v[24:25], v[24:25], v[52:53]
	s_waitcnt vmcnt(3)
	v_pk_add_f32 v[26:27], v[26:27], v[58:59]
	v_pk_add_f32 v[24:25], v[24:25], v[56:57]
	s_waitcnt vmcnt(2)
	v_pk_add_f32 v[26:27], v[26:27], v[62:63]
	v_pk_add_f32 v[24:25], v[24:25], v[60:61]
	s_waitcnt vmcnt(1)
	v_pk_add_f32 v[26:27], v[26:27], v[120:121]
	v_pk_add_f32 v[24:25], v[24:25], v[118:119]
	s_waitcnt vmcnt(0)
	v_pk_add_f32 v[26:27], v[26:27], v[132:133]
	v_pk_add_f32 v[24:25], v[24:25], v[130:131]

; __device__ __forceinline__ void ln_load_row(const Params& p, const float* src, int which, int r, int lane, f32x4 (&x)[8]) {
;     ...
;   for (int k = 0; k < 8; ++k) {
;     const int wg = gid * 64 + k * gsz + (pm - fm), off = wg % 36, xcd = wg / 36;
;     if (off >= 32) {
;       const int j = (off - 32) * 8 + xcd;
;       f32x4 v = *(const f32x4*)(rs + 256 * k + 4 * lane) * ALPHA;
;       const float* pp = part + (size_t)j * 8 * 65536 + (r & 255) * 256 + 4 * lane;
;       f32x4 t[8];
; #pragma unroll
;       for (int q = 0; q < 8; ++q) t[q] = *(const f32x4*)(pp + (size_t)q * 65536);
; #pragma unroll
;       for (int q = 0; q < 8; ++q) v += t[q];
;       x[k] = v;
;     } else x[k] = *(const f32x4*)(s + 256 * k + 4 * lane);
.LBB0_98:
	s_andn2_saveexec_b64 s[36:37], s[36:37]
	s_cbranch_execz .LBB0_100
	s_waitcnt vmcnt(0)
	v_lshlrev_b32_e32 v32, 3, v38
	s_movk_i32 s29, 0xff00
	v_add3_u32 v38, v37, v32, s29
	v_ashrrev_i32_e32 v39, 31, v38
	v_lshlrev_b64 v[38:39], 21, v[38:39]
	v_lshl_add_u64 v[38:39], v[116:117], 0, v[38:39]
	v_add_co_u32_e32 v48, vcc, 0x40000, v38
	global_load_dwordx4 v[32:35], v[114:115], off offset:1024
	s_nop 0
	v_addc_co_u32_e32 v49, vcc, 0, v39, vcc
	v_add_co_u32_e32 v52, vcc, 0x80000, v38
	global_load_dwordx4 v[44:47], v[38:39], off
	s_nop 0
	global_load_dwordx4 v[48:51], v[48:49], off
	v_addc_co_u32_e32 v53, vcc, 0, v39, vcc
	v_add_co_u32_e32 v56, vcc, 0xc0000, v38
	s_nop 1
	v_addc_co_u32_e32 v57, vcc, 0, v39, vcc
	v_add_co_u32_e32 v62, vcc, 0x100000, v38
	global_load_dwordx4 v[52:55], v[52:53], off
	s_nop 0
	global_load_dwordx4 v[56:59], v[56:57], off
	v_addc_co_u32_e32 v63, vcc, 0, v39, vcc
	v_add_co_u32_e32 v122, vcc, 0x140000, v38
	s_nop 0
	s_nop 1
	v_addc_co_u32_e32 v123, vcc, 0, v39, vcc
	global_load_dwordx4 v[118:121], v[62:63], off
	global_load_dwordx4 v[130:133], v[122:123], off
	v_add_co_u32_e32 v62, vcc, 0x180000, v38
	s_nop 1
	v_addc_co_u32_e32 v63, vcc, 0, v39, vcc
	v_add_co_u32_e32 v38, vcc, 0x1c0000, v38
	global_load_dwordx4 v[134:137], v[62:63], off
	s_nop 0
	v_addc_co_u32_e32 v39, vcc, 0, v39, vcc
	global_load_dwordx4 v[138:141], v[38:39], off
	s_waitcnt vmcnt(7)
	v_pk_fma_f32 v[34:35], v[34:35], s[2:3], v[46:47] op_sel_hi:[1,0,1]
	v_pk_fma_f32 v[32:33], v[32:33], s[2:3], v[44:45] op_sel_hi:[1,0,1]
	s_waitcnt vmcnt(6)
	v_pk_add_f32 v[34:35], v[34:35], v[50:51]
	v_pk_add_f32 v[32:33], v[32:33], v[48:49]
	s_waitcnt vmcnt(5)
	v_pk_add_f32 v[34:35], v[34:35], v[54:55]
	v_pk_add_f32 v[32:33], v[32:33], v[52:53]
	s_waitcnt vmcnt(4)
	v_pk_add_f32 v[34:35], v[34:35], v[58:59]
	v_pk_add_f32 v[32:33], v[32:33], v[56:57]
	s_waitcnt vmcnt(3)
	v_pk_add_f32 v[34:35], v[34:35], v[120:121]
	v_pk_add_f32 v[32:33], v[32:33], v[118:119]
	s_waitcnt vmcnt(2)
	v_pk_add_f32 v[34:35], v[34:35], v[132:133]
	v_pk_add_f32 v[32:33], v[32:33], v[130:131]
	s_waitcnt vmcnt(1)
	v_pk_add_f32 v[34:35], v[34:35], v[136:137]
	v_pk_add_f32 v[32:33], v[32:33], v[134:135]
	s_waitcnt vmcnt(0)
	v_pk_add_f32 v[34:35], v[34:35], v[140:141]
	v_pk_add_f32 v[32:33], v[32:33], v[138:139]

; __device__ __forceinline__ void ln_load_row(const Params& p, const float* src, int which, int r, int lane, f32x4 (&x)[8]) {
;     ...
;   for (int k = 0; k < 8; ++k) {
;     const int wg = gid * 64 + k * gsz + (pm - fm), off = wg % 36, xcd = wg / 36;
;     if (off >= 32) {
;       const int j = (off - 32) * 8 + xcd;
;       f32x4 v = *(const f32x4*)(rs + 256 * k + 4 * lane) * ALPHA;
;       const float* pp = part + (size_t)j * 8 * 65536 + (r & 255) * 256 + 4 * lane;
;       f32x4 t[8];
; #pragma unroll
;       for (int q = 0; q < 8; ++q) t[q] = *(const f32x4*)(pp + (size_t)q * 65536);
; #pragma unroll
;       for (int q = 0; q < 8; ++q) v += t[q];
;       x[k] = v;
;     } else x[k] = *(const f32x4*)(s + 256 * k + 4 * lane);
.LBB0_102:
	s_andn2_saveexec_b64 s[36:37], s[36:37]
	s_cbranch_execz .LBB0_104
	s_waitcnt vmcnt(0)
	v_lshlrev_b32_e32 v36, 3, v46
	s_movk_i32 s29, 0xff00
	v_add3_u32 v46, v45, v36, s29
	v_ashrrev_i32_e32 v47, 31, v46
	v_lshlrev_b64 v[46:47], 21, v[46:47]
	v_lshl_add_u64 v[58:59], v[116:117], 0, v[46:47]
	v_add_co_u32_e32 v50, vcc, 0x40000, v58
	global_load_dwordx4 v[36:39], v[114:115], off offset:2048
	s_nop 0
	v_addc_co_u32_e32 v51, vcc, 0, v59, vcc
	v_add_co_u32_e32 v54, vcc, 0x80000, v58
	global_load_dwordx4 v[46:49], v[58:59], off
	s_nop 0
	global_load_dwordx4 v[50:53], v[50:51], off
	v_addc_co_u32_e32 v55, vcc, 0, v59, vcc
	v_add_co_u32_e32 v62, vcc, 0xc0000, v58
	s_nop 1
	v_addc_co_u32_e32 v63, vcc, 0, v59, vcc
	global_load_dwordx4 v[54:57], v[54:55], off
	s_nop 0
	global_load_dwordx4 v[118:121], v[62:63], off
	v_add_co_u32_e32 v62, vcc, 0x100000, v58
	s_nop 0
	s_nop 1
	v_addc_co_u32_e32 v63, vcc, 0, v59, vcc
	v_add_co_u32_e32 v122, vcc, 0x140000, v58
	s_nop 1
	v_addc_co_u32_e32 v123, vcc, 0, v59, vcc
	global_load_dwordx4 v[130:133], v[62:63], off
	global_load_dwordx4 v[134:137], v[122:123], off
	v_add_co_u32_e32 v62, vcc, 0x180000, v58
	s_nop 0
	s_nop 1
	v_addc_co_u32_e32 v63, vcc, 0, v59, vcc
	v_add_co_u32_e32 v58, vcc, 0x1c0000, v58
	global_load_dwordx4 v[138:141], v[62:63], off
	s_nop 0
	v_addc_co_u32_e32 v59, vcc, 0, v59, vcc
	global_load_dwordx4 v[142:145], v[58:59], off
	s_waitcnt vmcnt(7)
	v_pk_fma_f32 v[38:39], v[38:39], s[2:3], v[48:49] op_sel_hi:[1,0,1]
	v_pk_fma_f32 v[36:37], v[36:37], s[2:3], v[46:47] op_sel_hi:[1,0,1]
	s_waitcnt vmcnt(6)
	v_pk_add_f32 v[38:39], v[38:39], v[52:53]
	v_pk_add_f32 v[36:37], v[36:37], v[50:51]
	s_waitcnt vmcnt(5)
	v_pk_add_f32 v[38:39], v[38:39], v[56:57]
	v_pk_add_f32 v[36:37], v[36:37], v[54:55]
	s_waitcnt vmcnt(4)
	v_pk_add_f32 v[38:39], v[38:39], v[120:121]
	v_pk_add_f32 v[36:37], v[36:37], v[118:119]
	s_waitcnt vmcnt(3)
	v_pk_add_f32 v[38:39], v[38:39], v[132:133]
	v_pk_add_f32 v[36:37], v[36:37], v[130:131]
	s_waitcnt vmcnt(2)
	v_pk_add_f32 v[38:39], v[38:39], v[136:137]
	v_pk_add_f32 v[36:37], v[36:37], v[134:135]
	s_waitcnt vmcnt(1)
	v_pk_add_f32 v[38:39], v[38:39], v[140:141]
	v_pk_add_f32 v[36:37], v[36:37], v[138:139]
	s_waitcnt vmcnt(0)
	v_pk_add_f32 v[38:39], v[38:39], v[144:145]
	v_pk_add_f32 v[36:37], v[36:37], v[142:143]

; __device__ __forceinline__ void ln_load_row(const Params& p, const float* src, int which, int r, int lane, f32x4 (&x)[8]) {
;     ...
;     const int wg = gid * 64 + k * gsz + (pm - fm), off = wg % 36, xcd = wg / 36;
;     if (off >= 32) {
;       const int j = (off - 32) * 8 + xcd;
;       f32x4 v = *(const f32x4*)(rs + 256 * k + 4 * lane) * ALPHA;
;       const float* pp = part + (size_t)j * 8 * 65536 + (r & 255) * 256 + 4 * lane;
;       f32x4 t[8];
; #pragma unroll
;       for (int q = 0; q < 8; ++q) t[q] = *(const f32x4*)(pp + (size_t)q * 65536);
; #pragma unroll
;       for (int q = 0; q < 8; ++q) v += t[q];
;       x[k] = v;
.LBB0_106:
	s_andn2_saveexec_b64 s[36:37], s[36:37]
	s_cbranch_execz .LBB0_108
	s_waitcnt vmcnt(0)
	v_lshlrev_b32_e32 v44, 3, v50
	s_movk_i32 s29, 0xff00
	v_add3_u32 v50, v49, v44, s29
	v_ashrrev_i32_e32 v51, 31, v50
	v_lshlrev_b64 v[50:51], 21, v[50:51]
	v_lshl_add_u64 v[58:59], v[116:117], 0, v[50:51]
	v_add_co_u32_e32 v54, vcc, 0x40000, v58
	global_load_dwordx4 v[44:47], v[114:115], off offset:3072
	s_nop 0
	v_addc_co_u32_e32 v55, vcc, 0, v59, vcc
	v_add_co_u32_e32 v62, vcc, 0x80000, v58
	global_load_dwordx4 v[50:53], v[58:59], off
	s_nop 0
	global_load_dwordx4 v[54:57], v[54:55], off
	v_addc_co_u32_e32 v63, vcc, 0, v59, vcc
	v_add_co_u32_e32 v122, vcc, 0xc0000, v58
	s_nop 1
	v_addc_co_u32_e32 v123, vcc, 0, v59, vcc
	global_load_dwordx4 v[118:121], v[62:63], off
	global_load_dwordx4 v[130:133], v[122:123], off
	v_add_co_u32_e32 v62, vcc, 0x100000, v58
	s_nop 0
	s_nop 1
	v_addc_co_u32_e32 v63, vcc, 0, v59, vcc
	v_add_co_u32_e32 v122, vcc, 0x140000, v58
	s_nop 1
	v_addc_co_u32_e32 v123, vcc, 0, v59, vcc
	global_load_dwordx4 v[134:137], v[62:63], off
	global_load_dwordx4 v[138:141], v[122:123], off
	v_add_co_u32_e32 v62, vcc, 0x180000, v58
	s_nop 0
	s_nop 1
	v_addc_co_u32_e32 v63, vcc, 0, v59, vcc
	v_add_co_u32_e32 v58, vcc, 0x1c0000, v58
	global_load_dwordx4 v[142:145], v[62:63], off
	s_nop 0
	v_addc_co_u32_e32 v59, vcc, 0, v59, vcc
	global_load_dwordx4 v[146:149], v[58:59], off
	s_waitcnt vmcnt(7)
	v_pk_fma_f32 v[46:47], v[46:47], s[2:3], v[52:53] op_sel_hi:[1,0,1]
	v_pk_fma_f32 v[44:45], v[44:45], s[2:3], v[50:51] op_sel_hi:[1,0,1]
	s_waitcnt vmcnt(6)
	v_pk_add_f32 v[46:47], v[46:47], v[56:57]
	v_pk_add_f32 v[44:45], v[44:45], v[54:55]
	s_waitcnt vmcnt(5)
	v_pk_add_f32 v[46:47], v[46:47], v[120:121]
	v_pk_add_f32 v[44:45], v[44:45], v[118:119]
	s_waitcnt vmcnt(4)
	v_pk_add_f32 v[46:47], v[46:47], v[132:133]
	v_pk_add_f32 v[44:45], v[44:45], v[130:131]
	s_waitcnt vmcnt(3)
	v_pk_add_f32 v[46:47], v[46:47], v[136:137]
	v_pk_add_f32 v[44:45], v[44:45], v[134:135]
	s_waitcnt vmcnt(2)
	v_pk_add_f32 v[46:47], v[46:47], v[140:141]
	v_pk_add_f32 v[44:45], v[44:45], v[138:139]
	s_waitcnt vmcnt(1)
	v_pk_add_f32 v[46:47], v[46:47], v[144:145]
	v_pk_add_f32 v[44:45], v[44:45], v[142:143]
	s_waitcnt vmcnt(0)
	v_pk_add_f32 v[46:47], v[46:47], v[148:149]
	v_pk_add_f32 v[44:45], v[44:45], v[146:147]

; __device__ __forceinline__ void ln_load_row(const Params& p, const float* src, int which, int r, int lane, f32x4 (&x)[8]) {
;     ...
;     const int wg = gid * 64 + k * gsz + (pm - fm), off = wg % 36, xcd = wg / 36;
;     if (off >= 32) {
;       const int j = (off - 32) * 8 + xcd;
;       f32x4 v = *(const f32x4*)(rs + 256 * k + 4 * lane) * ALPHA;
;       const float* pp = part + (size_t)j * 8 * 65536 + (r & 255) * 256 + 4 * lane;
;       f32x4 t[8];
; #pragma unroll
;       for (int q = 0; q < 8; ++q) t[q] = *(const f32x4*)(pp + (size_t)q * 65536);
; #pragma unroll
;       for (int q = 0; q < 8; ++q) v += t[q];
;       x[k] = v;
.LBB0_110:
	s_andn2_saveexec_b64 s[36:37], s[36:37]
	s_cbranch_execz .LBB0_112
	s_waitcnt vmcnt(0)
	v_lshlrev_b32_e32 v48, 3, v54
	s_movk_i32 s29, 0xff00
	v_add3_u32 v54, v53, v48, s29
	v_ashrrev_i32_e32 v55, 31, v54
	v_add_co_u32_e32 v48, vcc, 0x1000, v114
	v_lshlrev_b64 v[54:55], 21, v[54:55]
	s_nop 0
	v_addc_co_u32_e32 v49, vcc, 0, v115, vcc
	v_lshl_add_u64 v[58:59], v[116:117], 0, v[54:55]
	v_add_co_u32_e32 v62, vcc, 0x40000, v58
	global_load_dwordx4 v[48:51], v[48:49], off
	s_nop 0
	v_addc_co_u32_e32 v63, vcc, 0, v59, vcc
	global_load_dwordx4 v[54:57], v[58:59], off
	global_load_dwordx4 v[118:121], v[62:63], off
	v_add_co_u32_e32 v62, vcc, 0x80000, v58
	s_nop 1
	v_addc_co_u32_e32 v63, vcc, 0, v59, vcc
	v_add_co_u32_e32 v122, vcc, 0xc0000, v58
	s_nop 0
	s_nop 1
	v_addc_co_u32_e32 v123, vcc, 0, v59, vcc
	global_load_dwordx4 v[130:133], v[62:63], off
	global_load_dwordx4 v[134:137], v[122:123], off
	v_add_co_u32_e32 v62, vcc, 0x100000, v58
	s_nop 1
	v_addc_co_u32_e32 v63, vcc, 0, v59, vcc
	v_add_co_u32_e32 v122, vcc, 0x140000, v58
	s_nop 0
	s_nop 1
	v_addc_co_u32_e32 v123, vcc, 0, v59, vcc
	global_load_dwordx4 v[138:141], v[62:63], off
	global_load_dwordx4 v[142:145], v[122:123], off
	v_add_co_u32_e32 v62, vcc, 0x180000, v58
	s_nop 1
	v_addc_co_u32_e32 v63, vcc, 0, v59, vcc
	v_add_co_u32_e32 v58, vcc, 0x1c0000, v58
	global_load_dwordx4 v[146:149], v[62:63], off
	s_nop 0
	v_addc_co_u32_e32 v59, vcc, 0, v59, vcc
	global_load_dwordx4 v[150:153], v[58:59], off
	s_waitcnt vmcnt(7)
	v_pk_fma_f32 v[50:51], v[50:51], s[2:3], v[56:57] op_sel_hi:[1,0,1]
	v_pk_fma_f32 v[48:49], v[48:49], s[2:3], v[54:55] op_sel_hi:[1,0,1]
	s_waitcnt vmcnt(6)
	v_pk_add_f32 v[50:51], v[50:51], v[120:121]
	v_pk_add_f32 v[48:49], v[48:49], v[118:119]
	s_waitcnt vmcnt(5)
	v_pk_add_f32 v[50:51], v[50:51], v[132:133]
	v_pk_add_f32 v[48:49], v[48:49], v[130:131]
	s_waitcnt vmcnt(4)
	v_pk_add_f32 v[50:51], v[50:51], v[136:137]
	v_pk_add_f32 v[48:49], v[48:49], v[134:135]
	s_waitcnt vmcnt(3)
	v_pk_add_f32 v[50:51], v[50:51], v[140:141]
	v_pk_add_f32 v[48:49], v[48:49], v[138:139]
	s_waitcnt vmcnt(2)
	v_pk_add_f32 v[50:51], v[50:51], v[144:145]
	v_pk_add_f32 v[48:49], v[48:49], v[142:143]
	s_waitcnt vmcnt(1)
	v_pk_add_f32 v[50:51], v[50:51], v[148:149]
	v_pk_add_f32 v[48:49], v[48:49], v[146:147]
	s_waitcnt vmcnt(0)
	v_pk_add_f32 v[50:51], v[50:51], v[152:153]
	v_pk_add_f32 v[48:49], v[48:49], v[150:151]

; __device__ __forceinline__ void ln_load_row(const Params& p, const float* src, int which, int r, int lane, f32x4 (&x)[8]) {
;     ...
;     const int wg = gid * 64 + k * gsz + (pm - fm), off = wg % 36, xcd = wg / 36;
;     if (off >= 32) {
;       const int j = (off - 32) * 8 + xcd;
;       f32x4 v = *(const f32x4*)(rs + 256 * k + 4 * lane) * ALPHA;
;       const float* pp = part + (size_t)j * 8 * 65536 + (r & 255) * 256 + 4 * lane;
;       f32x4 t[8];
; #pragma unroll
;       for (int q = 0; q < 8; ++q) t[q] = *(const f32x4*)(pp + (size_t)q * 65536);
; #pragma unroll
;       for (int q = 0; q < 8; ++q) v += t[q];
;       x[k] = v;
.LBB0_114:
	s_andn2_saveexec_b64 s[36:37], s[36:37]
	s_cbranch_execz .LBB0_116
	s_waitcnt vmcnt(0)
	v_lshlrev_b32_e32 v52, 3, v58
	s_movk_i32 s29, 0xff00
	v_add3_u32 v58, v57, v52, s29
	v_ashrrev_i32_e32 v59, 31, v58
	v_add_co_u32_e32 v52, vcc, 0x1000, v114
	v_lshlrev_b64 v[58:59], 21, v[58:59]
	s_nop 0
	v_addc_co_u32_e32 v53, vcc, 0, v115, vcc
	v_lshl_add_u64 v[58:59], v[116:117], 0, v[58:59]
	v_add_co_u32_e32 v62, vcc, 0x40000, v58
	global_load_dwordx4 v[52:55], v[52:53], off offset:1024
	s_nop 0
	v_addc_co_u32_e32 v63, vcc, 0, v59, vcc
	global_load_dwordx4 v[118:121], v[58:59], off
	global_load_dwordx4 v[130:133], v[62:63], off
	v_add_co_u32_e32 v62, vcc, 0x80000, v58
	s_nop 1
	v_addc_co_u32_e32 v63, vcc, 0, v59, vcc
	v_add_co_u32_e32 v122, vcc, 0xc0000, v58
	s_nop 0
	s_nop 1
	v_addc_co_u32_e32 v123, vcc, 0, v59, vcc
	global_load_dwordx4 v[134:137], v[62:63], off
	global_load_dwordx4 v[138:141], v[122:123], off
	v_add_co_u32_e32 v62, vcc, 0x100000, v58
	s_nop 1
	v_addc_co_u32_e32 v63, vcc, 0, v59, vcc
	v_add_co_u32_e32 v122, vcc, 0x140000, v58
	s_nop 0
	s_nop 1
	v_addc_co_u32_e32 v123, vcc, 0, v59, vcc
	global_load_dwordx4 v[142:145], v[62:63], off
	global_load_dwordx4 v[146:149], v[122:123], off
	v_add_co_u32_e32 v62, vcc, 0x180000, v58
	s_nop 1
	v_addc_co_u32_e32 v63, vcc, 0, v59, vcc
	v_add_co_u32_e32 v58, vcc, 0x1c0000, v58
	global_load_dwordx4 v[150:153], v[62:63], off
	s_nop 0
	v_addc_co_u32_e32 v59, vcc, 0, v59, vcc
	global_load_dwordx4 v[154:157], v[58:59], off
	s_waitcnt vmcnt(7)
	v_pk_fma_f32 v[54:55], v[54:55], s[2:3], v[120:121] op_sel_hi:[1,0,1]
	v_pk_fma_f32 v[52:53], v[52:53], s[2:3], v[118:119] op_sel_hi:[1,0,1]
	s_waitcnt vmcnt(6)
	v_pk_add_f32 v[54:55], v[54:55], v[132:133]
	v_pk_add_f32 v[52:53], v[52:53], v[130:131]
	s_waitcnt vmcnt(5)
	v_pk_add_f32 v[54:55], v[54:55], v[136:137]
	v_pk_add_f32 v[52:53], v[52:53], v[134:135]
	s_waitcnt vmcnt(4)
	v_pk_add_f32 v[54:55], v[54:55], v[140:141]
	v_pk_add_f32 v[52:53], v[52:53], v[138:139]
	s_waitcnt vmcnt(3)
	v_pk_add_f32 v[54:55], v[54:55], v[144:145]
	v_pk_add_f32 v[52:53], v[52:53], v[142:143]
	s_waitcnt vmcnt(2)
	v_pk_add_f32 v[54:55], v[54:55], v[148:149]
	v_pk_add_f32 v[52:53], v[52:53], v[146:147]
	s_waitcnt vmcnt(1)
	v_pk_add_f32 v[54:55], v[54:55], v[152:153]
	v_pk_add_f32 v[52:53], v[52:53], v[150:151]
	s_waitcnt vmcnt(0)
	v_pk_add_f32 v[54:55], v[54:55], v[156:157]
	v_pk_add_f32 v[52:53], v[52:53], v[154:155]

; __device__ __forceinline__ void ln_load_row(const Params& p, const float* src, int which, int r, int lane, f32x4 (&x)[8]) {
;     ...
;     const int wg = gid * 64 + k * gsz + (pm - fm), off = wg % 36, xcd = wg / 36;
;     if (off >= 32) {
;       const int j = (off - 32) * 8 + xcd;
;       f32x4 v = *(const f32x4*)(rs + 256 * k + 4 * lane) * ALPHA;
;       const float* pp = part + (size_t)j * 8 * 65536 + (r & 255) * 256 + 4 * lane;
;       f32x4 t[8];
; #pragma unroll
;       for (int q = 0; q < 8; ++q) t[q] = *(const f32x4*)(pp + (size_t)q * 65536);
; #pragma unroll
;       for (int q = 0; q < 8; ++q) v += t[q];
;       x[k] = v;
.LBB0_118:
	s_andn2_saveexec_b64 s[36:37], s[36:37]
	s_cbranch_execz .LBB0_120
	s_waitcnt vmcnt(0)
	v_lshlrev_b32_e32 v56, 3, v63
	s_movk_i32 s29, 0xff00
	v_add3_u32 v62, v62, v56, s29
	v_ashrrev_i32_e32 v63, 31, v62
	v_add_co_u32_e32 v56, vcc, 0x1000, v114
	v_lshlrev_b64 v[62:63], 21, v[62:63]
	s_nop 0
	v_addc_co_u32_e32 v57, vcc, 0, v115, vcc
	v_lshl_add_u64 v[62:63], v[116:117], 0, v[62:63]
	v_add_co_u32_e32 v122, vcc, 0x40000, v62
	global_load_dwordx4 v[56:59], v[56:57], off offset:2048
	s_nop 0
	v_addc_co_u32_e32 v123, vcc, 0, v63, vcc
	global_load_dwordx4 v[118:121], v[62:63], off
	global_load_dwordx4 v[130:133], v[122:123], off
	v_add_co_u32_e32 v122, vcc, 0x80000, v62
	s_nop 1
	v_addc_co_u32_e32 v123, vcc, 0, v63, vcc
	v_add_co_u32_e32 v138, vcc, 0xc0000, v62
	s_nop 0
	s_nop 1
	v_addc_co_u32_e32 v139, vcc, 0, v63, vcc
	global_load_dwordx4 v[134:137], v[122:123], off
	s_nop 0
	global_load_dwordx4 v[138:141], v[138:139], off
	v_add_co_u32_e32 v122, vcc, 0x100000, v62
	s_nop 1
	v_addc_co_u32_e32 v123, vcc, 0, v63, vcc
	v_add_co_u32_e32 v146, vcc, 0x140000, v62
	s_nop 0
	s_nop 1
	v_addc_co_u32_e32 v147, vcc, 0, v63, vcc
	global_load_dwordx4 v[142:145], v[122:123], off
	s_nop 0
	global_load_dwordx4 v[146:149], v[146:147], off
	v_add_co_u32_e32 v122, vcc, 0x180000, v62
	s_nop 1
	v_addc_co_u32_e32 v123, vcc, 0, v63, vcc
	v_add_co_u32_e32 v62, vcc, 0x1c0000, v62
	global_load_dwordx4 v[150:153], v[122:123], off
	s_nop 0
	v_addc_co_u32_e32 v63, vcc, 0, v63, vcc
	global_load_dwordx4 v[154:157], v[62:63], off
	s_waitcnt vmcnt(7)
	v_pk_fma_f32 v[58:59], v[58:59], s[2:3], v[120:121] op_sel_hi:[1,0,1]
	v_pk_fma_f32 v[56:57], v[56:57], s[2:3], v[118:119] op_sel_hi:[1,0,1]
	s_waitcnt vmcnt(6)
	v_pk_add_f32 v[58:59], v[58:59], v[132:133]
	v_pk_add_f32 v[56:57], v[56:57], v[130:131]
	s_waitcnt vmcnt(5)
	v_pk_add_f32 v[58:59], v[58:59], v[136:137]
	v_pk_add_f32 v[56:57], v[56:57], v[134:135]
	s_waitcnt vmcnt(4)
	v_pk_add_f32 v[58:59], v[58:59], v[140:141]
	v_pk_add_f32 v[56:57], v[56:57], v[138:139]
	s_waitcnt vmcnt(3)
	v_pk_add_f32 v[58:59], v[58:59], v[144:145]
	v_pk_add_f32 v[56:57], v[56:57], v[142:143]
	s_waitcnt vmcnt(2)
	v_pk_add_f32 v[58:59], v[58:59], v[148:149]
	v_pk_add_f32 v[56:57], v[56:57], v[146:147]
	s_waitcnt vmcnt(1)
	v_pk_add_f32 v[58:59], v[58:59], v[152:153]
	v_pk_add_f32 v[56:57], v[56:57], v[150:151]
	s_waitcnt vmcnt(0)
	v_pk_add_f32 v[58:59], v[58:59], v[156:157]
	v_pk_add_f32 v[56:57], v[56:57], v[154:155]

; __device__ __forceinline__ void ln_load_row(const Params& p, const float* src, int which, int r, int lane, f32x4 (&x)[8]) {
;     ...
;     const int wg = gid * 64 + k * gsz + (pm - fm), off = wg % 36, xcd = wg / 36;
;     if (off >= 32) {
;       const int j = (off - 32) * 8 + xcd;
;       f32x4 v = *(const f32x4*)(rs + 256 * k + 4 * lane) * ALPHA;
;       const float* pp = part + (size_t)j * 8 * 65536 + (r & 255) * 256 + 4 * lane;
;       f32x4 t[8];
; #pragma unroll
;       for (int q = 0; q < 8; ++q) t[q] = *(const f32x4*)(pp + (size_t)q * 65536);
; #pragma unroll
;       for (int q = 0; q < 8; ++q) v += t[q];
;       x[k] = v;
.LBB0_122:
	s_andn2_saveexec_b64 s[36:37], s[36:37]
	s_cbranch_execz .LBB0_124
	s_waitcnt vmcnt(0)
	v_lshlrev_b32_e32 v60, 3, v103
	s_movk_i32 s29, 0xff00
	v_add3_u32 v118, v67, v60, s29
	v_add_co_u32_e32 v60, vcc, 0x1000, v114
	v_ashrrev_i32_e32 v119, 31, v118
	s_nop 0
	v_addc_co_u32_e32 v61, vcc, 0, v115, vcc
	v_lshlrev_b64 v[114:115], 21, v[118:119]
	v_lshl_add_u64 v[122:123], v[116:117], 0, v[114:115]
	v_add_co_u32_e32 v118, vcc, 0x40000, v122
	global_load_dwordx4 v[60:63], v[60:61], off offset:3072
	s_nop 0
	v_addc_co_u32_e32 v119, vcc, 0, v123, vcc
	v_add_co_u32_e32 v130, vcc, 0x80000, v122
	global_load_dwordx4 v[114:117], v[122:123], off
	s_nop 0
	global_load_dwordx4 v[118:121], v[118:119], off
	v_addc_co_u32_e32 v131, vcc, 0, v123, vcc
	v_add_co_u32_e32 v134, vcc, 0xc0000, v122
	s_nop 1
	v_addc_co_u32_e32 v135, vcc, 0, v123, vcc
	v_add_co_u32_e32 v138, vcc, 0x100000, v122
	global_load_dwordx4 v[130:133], v[130:131], off
	s_nop 0
	global_load_dwordx4 v[134:137], v[134:135], off
	v_addc_co_u32_e32 v139, vcc, 0, v123, vcc
	v_add_co_u32_e32 v142, vcc, 0x140000, v122
	s_nop 0
	s_nop 1
	v_addc_co_u32_e32 v143, vcc, 0, v123, vcc
	v_add_co_u32_e32 v146, vcc, 0x180000, v122
	global_load_dwordx4 v[138:141], v[138:139], off
	s_nop 0
	global_load_dwordx4 v[142:145], v[142:143], off
	v_addc_co_u32_e32 v147, vcc, 0, v123, vcc
	v_add_co_u32_e32 v122, vcc, 0x1c0000, v122
	global_load_dwordx4 v[146:149], v[146:147], off
	s_nop 0
	v_addc_co_u32_e32 v123, vcc, 0, v123, vcc
	global_load_dwordx4 v[150:153], v[122:123], off
	s_waitcnt vmcnt(7)
	v_pk_fma_f32 v[62:63], v[62:63], s[2:3], v[116:117] op_sel_hi:[1,0,1]
	v_pk_fma_f32 v[60:61], v[60:61], s[2:3], v[114:115] op_sel_hi:[1,0,1]
	s_waitcnt vmcnt(6)
	v_pk_add_f32 v[62:63], v[62:63], v[120:121]
	v_pk_add_f32 v[60:61], v[60:61], v[118:119]
	s_waitcnt vmcnt(5)
	v_pk_add_f32 v[62:63], v[62:63], v[132:133]
	v_pk_add_f32 v[60:61], v[60:61], v[130:131]
	s_waitcnt vmcnt(4)
	v_pk_add_f32 v[62:63], v[62:63], v[136:137]
	v_pk_add_f32 v[60:61], v[60:61], v[134:135]
	s_waitcnt vmcnt(3)
	v_pk_add_f32 v[62:63], v[62:63], v[140:141]
	v_pk_add_f32 v[60:61], v[60:61], v[138:139]
	s_waitcnt vmcnt(2)
	v_pk_add_f32 v[62:63], v[62:63], v[144:145]
	v_pk_add_f32 v[60:61], v[60:61], v[142:143]
	s_waitcnt vmcnt(1)
	v_pk_add_f32 v[62:63], v[62:63], v[148:149]
	v_pk_add_f32 v[60:61], v[60:61], v[146:147]
	s_waitcnt vmcnt(0)
	v_pk_add_f32 v[62:63], v[62:63], v[152:153]
	v_pk_add_f32 v[60:61], v[60:61], v[150:151]

; __device__ __forceinline__ void ln_load_row(const Params& p, const float* src, int which, int r, int lane, f32x4 (&x)[8]) {
;   const float* part = (const float*)(p.ws + WS_PART);
;   const float* s = src + (size_t)r * 2048;
;   const float* rs = which == 0 ? (r < TOKP ? p.in[0] + (size_t)r * 2048 : p.in[1] + (size_t)(r - TOKP) * 2048) : (const float*)(p.ws + WS_X1) + (size_t)r * 2048;
;   const int pm = r >> 8, gid = pm >> 3, fm = gid * 8, gsz = (36 - fm) < 8 ? (36 - fm) : 8;
; #pragma unroll
;   for (int k = 0; k < 8; ++k) {
;     const int wg = gid * 64 + k * gsz + (pm - fm), off = wg % 36, xcd = wg / 36;
;     if (off >= 32) {
;       const int j = (off - 32) * 8 + xcd;
;       f32x4 v = *(const f32x4*)(rs + 256 * k + 4 * lane) * ALPHA;
;       const float* pp = part + (size_t)j * 8 * 65536 + (r & 255) * 256 + 4 * lane;
;       f32x4 t[8];
; #pragma unroll
;       for (int q = 0; q < 8; ++q) t[q] = *(const f32x4*)(pp + (size_t)q * 65536);
; #pragma unroll
;       for (int q = 0; q < 8; ++q) v += t[q];
;       x[k] = v;
.LBB0_127:
	s_or_saveexec_b64 s[38:39], s[38:39]
	v_add_u32_e32 v10, 0xffffe000, v114
	v_mov_b32_e32 v11, v65
	v_lshlrev_b64 v[10:11], 13, v[10:11]
	v_lshl_add_u64 v[4:5], s[4:5], 0, v[4:5]
	v_lshl_add_u64 v[10:11], s[6:7], 0, v[10:11]
	v_cndmask_b32_e32 v5, v11, v5, vcc
	v_cndmask_b32_e32 v4, v10, v4, vcc
	v_readlane_b32 s29, v255, 10
	v_lshl_add_u64 v[118:119], v[4:5], 0, v[64:65]
	v_mov_b32_e32 v5, v65
	v_add_u32_e32 v4, s29, v129
	v_and_b32_e32 v4, 0xff00, v4
	v_lshlrev_b32_e32 v4, 2, v4
	v_lshl_add_u64 v[120:121], v[92:93], 0, v[4:5]
	s_xor_b64 exec, exec, s[38:39]
	s_cbranch_execz .LBB0_129
	s_waitcnt vmcnt(0)
	v_lshlrev_b32_e32 v0, 3, v9
	s_movk_i32 s29, 0xff00
	v_add3_u32 v4, v8, v0, s29
	v_ashrrev_i32_e32 v5, 31, v4
	v_lshlrev_b64 v[4:5], 21, v[4:5]
	v_lshl_add_u64 v[4:5], v[120:121], 0, v[4:5]
	v_add_co_u32_e32 v12, vcc, 0x40000, v4
	global_load_dwordx4 v[0:3], v[118:119], off
	s_nop 0
	v_addc_co_u32_e32 v13, vcc, 0, v5, vcc
	v_add_co_u32_e32 v16, vcc, 0x80000, v4
	global_load_dwordx4 v[8:11], v[4:5], off
	s_nop 0
	global_load_dwordx4 v[12:15], v[12:13], off
	v_addc_co_u32_e32 v17, vcc, 0, v5, vcc
	v_add_co_u32_e32 v20, vcc, 0xc0000, v4
	s_nop 1
	v_addc_co_u32_e32 v21, vcc, 0, v5, vcc
	v_add_co_u32_e32 v28, vcc, 0x100000, v4
	global_load_dwordx4 v[16:19], v[16:17], off
	s_nop 0
	global_load_dwordx4 v[20:23], v[20:21], off
	v_addc_co_u32_e32 v29, vcc, 0, v5, vcc
	v_add_co_u32_e32 v40, vcc, 0x140000, v4
	s_nop 0
	s_nop 1
	v_addc_co_u32_e32 v41, vcc, 0, v5, vcc
	v_add_co_u32_e32 v122, vcc, 0x180000, v4
	global_load_dwordx4 v[28:31], v[28:29], off
	s_nop 0
	global_load_dwordx4 v[40:43], v[40:41], off
	v_addc_co_u32_e32 v123, vcc, 0, v5, vcc
	v_add_co_u32_e32 v4, vcc, 0x1c0000, v4
	global_load_dwordx4 v[130:133], v[122:123], off
	s_nop 0
	v_addc_co_u32_e32 v5, vcc, 0, v5, vcc
	global_load_dwordx4 v[134:137], v[4:5], off
	s_waitcnt vmcnt(7)
	v_pk_fma_f32 v[2:3], v[2:3], s[2:3], v[10:11] op_sel_hi:[1,0,1]
	v_pk_fma_f32 v[0:1], v[0:1], s[2:3], v[8:9] op_sel_hi:[1,0,1]
	s_waitcnt vmcnt(6)
	v_pk_add_f32 v[2:3], v[2:3], v[14:15]
	v_pk_add_f32 v[0:1], v[0:1], v[12:13]
	s_waitcnt vmcnt(5)
	v_pk_add_f32 v[2:3], v[2:3], v[18:19]
	v_pk_add_f32 v[0:1], v[0:1], v[16:17]
	s_waitcnt vmcnt(4)
	v_pk_add_f32 v[2:3], v[2:3], v[22:23]
	v_pk_add_f32 v[0:1], v[0:1], v[20:21]
	s_waitcnt vmcnt(3)
	v_pk_add_f32 v[2:3], v[2:3], v[30:31]
	v_pk_add_f32 v[0:1], v[0:1], v[28:29]
	s_waitcnt vmcnt(2)
	v_pk_add_f32 v[2:3], v[2:3], v[42:43]
	v_pk_add_f32 v[0:1], v[0:1], v[40:41]
	s_waitcnt vmcnt(1)
	v_pk_add_f32 v[2:3], v[2:3], v[132:133]
	v_pk_add_f32 v[0:1], v[0:1], v[130:131]
	s_waitcnt vmcnt(0)
	v_pk_add_f32 v[2:3], v[2:3], v[136:137]
	v_pk_add_f32 v[0:1], v[0:1], v[134:135]

; __device__ __forceinline__ void ln_load_row(const Params& p, const float* src, int which, int r, int lane, f32x4 (&x)[8]) {
;     ...
;     const int wg = gid * 64 + k * gsz + (pm - fm), off = wg % 36, xcd = wg / 36;
;     if (off >= 32) {
;       const int j = (off - 32) * 8 + xcd;
;       f32x4 v = *(const f32x4*)(rs + 256 * k + 4 * lane) * ALPHA;
;       const float* pp = part + (size_t)j * 8 * 65536 + (r & 255) * 256 + 4 * lane;
;       f32x4 t[8];
; #pragma unroll
;       for (int q = 0; q < 8; ++q) t[q] = *(const f32x4*)(pp + (size_t)q * 65536);
; #pragma unroll
;       for (int q = 0; q < 8; ++q) v += t[q];
;       x[k] = v;
.LBB0_131:
	s_andn2_saveexec_b64 s[38:39], s[38:39]
	s_cbranch_execz .LBB0_133
	s_waitcnt vmcnt(0)
	v_lshlrev_b32_e32 v4, 3, v10
	s_movk_i32 s29, 0xff00
	v_add3_u32 v10, v9, v4, s29
	v_ashrrev_i32_e32 v11, 31, v10
	v_lshlrev_b64 v[10:11], 21, v[10:11]
	v_lshl_add_u64 v[22:23], v[120:121], 0, v[10:11]
	v_add_co_u32_e32 v14, vcc, 0x40000, v22
	global_load_dwordx4 v[4:7], v[118:119], off offset:1024
	s_nop 0
	v_addc_co_u32_e32 v15, vcc, 0, v23, vcc
	v_add_co_u32_e32 v18, vcc, 0x80000, v22
	global_load_dwordx4 v[10:13], v[22:23], off
	s_nop 0
	global_load_dwordx4 v[14:17], v[14:15], off
	v_addc_co_u32_e32 v19, vcc, 0, v23, vcc
	v_add_co_u32_e32 v28, vcc, 0xc0000, v22
	s_nop 1
	v_addc_co_u32_e32 v29, vcc, 0, v23, vcc
	v_add_co_u32_e32 v42, vcc, 0x100000, v22
	global_load_dwordx4 v[18:21], v[18:19], off
	s_nop 0
	global_load_dwordx4 v[28:31], v[28:29], off
	v_addc_co_u32_e32 v43, vcc, 0, v23, vcc
	v_add_co_u32_e32 v122, vcc, 0x140000, v22
	s_nop 0
	s_nop 1
	v_addc_co_u32_e32 v123, vcc, 0, v23, vcc
	global_load_dwordx4 v[130:133], v[42:43], off
	global_load_dwordx4 v[134:137], v[122:123], off
	v_add_co_u32_e32 v42, vcc, 0x180000, v22
	s_nop 1
	v_addc_co_u32_e32 v43, vcc, 0, v23, vcc
	v_add_co_u32_e32 v22, vcc, 0x1c0000, v22
	global_load_dwordx4 v[138:141], v[42:43], off
	s_nop 0
	v_addc_co_u32_e32 v23, vcc, 0, v23, vcc
	global_load_dwordx4 v[142:145], v[22:23], off
	s_waitcnt vmcnt(7)
	v_pk_fma_f32 v[6:7], v[6:7], s[2:3], v[12:13] op_sel_hi:[1,0,1]
	v_pk_fma_f32 v[4:5], v[4:5], s[2:3], v[10:11] op_sel_hi:[1,0,1]
	s_waitcnt vmcnt(6)
	v_pk_add_f32 v[6:7], v[6:7], v[16:17]
	v_pk_add_f32 v[4:5], v[4:5], v[14:15]
	s_waitcnt vmcnt(5)
	v_pk_add_f32 v[6:7], v[6:7], v[20:21]
	v_pk_add_f32 v[4:5], v[4:5], v[18:19]
	s_waitcnt vmcnt(4)
	v_pk_add_f32 v[6:7], v[6:7], v[30:31]
	v_pk_add_f32 v[4:5], v[4:5], v[28:29]
	s_waitcnt vmcnt(3)
	v_pk_add_f32 v[6:7], v[6:7], v[132:133]
	v_pk_add_f32 v[4:5], v[4:5], v[130:131]
	s_waitcnt vmcnt(2)
	v_pk_add_f32 v[6:7], v[6:7], v[136:137]
	v_pk_add_f32 v[4:5], v[4:5], v[134:135]
	s_waitcnt vmcnt(1)
	v_pk_add_f32 v[6:7], v[6:7], v[140:141]
	v_pk_add_f32 v[4:5], v[4:5], v[138:139]
	s_waitcnt vmcnt(0)
	v_pk_add_f32 v[6:7], v[6:7], v[144:145]
	v_pk_add_f32 v[4:5], v[4:5], v[142:143]

; __device__ __forceinline__ void ln_load_row(const Params& p, const float* src, int which, int r, int lane, f32x4 (&x)[8]) {
;     ...
;     const int wg = gid * 64 + k * gsz + (pm - fm), off = wg % 36, xcd = wg / 36;
;     if (off >= 32) {
;       const int j = (off - 32) * 8 + xcd;
;       f32x4 v = *(const f32x4*)(rs + 256 * k + 4 * lane) * ALPHA;
;       const float* pp = part + (size_t)j * 8 * 65536 + (r & 255) * 256 + 4 * lane;
;       f32x4 t[8];
; #pragma unroll
;       for (int q = 0; q < 8; ++q) t[q] = *(const f32x4*)(pp + (size_t)q * 65536);
; #pragma unroll
;       for (int q = 0; q < 8; ++q) v += t[q];
;       x[k] = v;
.LBB0_135:
	s_andn2_saveexec_b64 s[38:39], s[38:39]
	s_cbranch_execz .LBB0_137
	s_waitcnt vmcnt(0)
	v_lshlrev_b32_e32 v8, 3, v14
	s_movk_i32 s29, 0xff00
	v_add3_u32 v14, v13, v8, s29
	v_ashrrev_i32_e32 v15, 31, v14
	v_lshlrev_b64 v[14:15], 21, v[14:15]
	v_lshl_add_u64 v[22:23], v[120:121], 0, v[14:15]
	v_add_co_u32_e32 v18, vcc, 0x40000, v22
	global_load_dwordx4 v[8:11], v[118:119], off offset:2048
	s_nop 0
	v_addc_co_u32_e32 v19, vcc, 0, v23, vcc
	v_add_co_u32_e32 v28, vcc, 0x80000, v22
	global_load_dwordx4 v[14:17], v[22:23], off
	s_nop 0
	global_load_dwordx4 v[18:21], v[18:19], off
	v_addc_co_u32_e32 v29, vcc, 0, v23, vcc
	v_add_co_u32_e32 v42, vcc, 0xc0000, v22
	s_nop 1
	v_addc_co_u32_e32 v43, vcc, 0, v23, vcc
	global_load_dwordx4 v[28:31], v[28:29], off
	s_nop 0
	global_load_dwordx4 v[130:133], v[42:43], off
	v_add_co_u32_e32 v42, vcc, 0x100000, v22
	s_nop 0
	s_nop 1
	v_addc_co_u32_e32 v43, vcc, 0, v23, vcc
	v_add_co_u32_e32 v122, vcc, 0x140000, v22
	s_nop 1
	v_addc_co_u32_e32 v123, vcc, 0, v23, vcc
	global_load_dwordx4 v[134:137], v[42:43], off
	global_load_dwordx4 v[138:141], v[122:123], off
	v_add_co_u32_e32 v42, vcc, 0x180000, v22
	s_nop 0
	s_nop 1
	v_addc_co_u32_e32 v43, vcc, 0, v23, vcc
	v_add_co_u32_e32 v22, vcc, 0x1c0000, v22
	global_load_dwordx4 v[142:145], v[42:43], off
	s_nop 0
	v_addc_co_u32_e32 v23, vcc, 0, v23, vcc
	global_load_dwordx4 v[146:149], v[22:23], off
	s_waitcnt vmcnt(7)
	v_pk_fma_f32 v[10:11], v[10:11], s[2:3], v[16:17] op_sel_hi:[1,0,1]
	v_pk_fma_f32 v[8:9], v[8:9], s[2:3], v[14:15] op_sel_hi:[1,0,1]
	s_waitcnt vmcnt(6)
	v_pk_add_f32 v[10:11], v[10:11], v[20:21]
	v_pk_add_f32 v[8:9], v[8:9], v[18:19]
	s_waitcnt vmcnt(5)
	v_pk_add_f32 v[10:11], v[10:11], v[30:31]
	v_pk_add_f32 v[8:9], v[8:9], v[28:29]
	s_waitcnt vmcnt(4)
	v_pk_add_f32 v[10:11], v[10:11], v[132:133]
	v_pk_add_f32 v[8:9], v[8:9], v[130:131]
	s_waitcnt vmcnt(3)
	v_pk_add_f32 v[10:11], v[10:11], v[136:137]
	v_pk_add_f32 v[8:9], v[8:9], v[134:135]
	s_waitcnt vmcnt(2)
	v_pk_add_f32 v[10:11], v[10:11], v[140:141]
	v_pk_add_f32 v[8:9], v[8:9], v[138:139]
	s_waitcnt vmcnt(1)
	v_pk_add_f32 v[10:11], v[10:11], v[144:145]
	v_pk_add_f32 v[8:9], v[8:9], v[142:143]
	s_waitcnt vmcnt(0)
	v_pk_add_f32 v[10:11], v[10:11], v[148:149]
	v_pk_add_f32 v[8:9], v[8:9], v[146:147]

; __device__ __forceinline__ void ln_load_row(const Params& p, const float* src, int which, int r, int lane, f32x4 (&x)[8]) {
;     ...
;     const int wg = gid * 64 + k * gsz + (pm - fm), off = wg % 36, xcd = wg / 36;
;     if (off >= 32) {
;       const int j = (off - 32) * 8 + xcd;
;       f32x4 v = *(const f32x4*)(rs + 256 * k + 4 * lane) * ALPHA;
;       const float* pp = part + (size_t)j * 8 * 65536 + (r & 255) * 256 + 4 * lane;
;       f32x4 t[8];
; #pragma unroll
;       for (int q = 0; q < 8; ++q) t[q] = *(const f32x4*)(pp + (size_t)q * 65536);
; #pragma unroll
;       for (int q = 0; q < 8; ++q) v += t[q];
;       x[k] = v;
.LBB0_139:
	s_andn2_saveexec_b64 s[38:39], s[38:39]
	s_cbranch_execz .LBB0_141
	s_waitcnt vmcnt(0)
	v_lshlrev_b32_e32 v12, 3, v18
	s_movk_i32 s29, 0xff00
	v_add3_u32 v18, v17, v12, s29
	v_ashrrev_i32_e32 v19, 31, v18
	v_lshlrev_b64 v[18:19], 21, v[18:19]
	v_lshl_add_u64 v[22:23], v[120:121], 0, v[18:19]
	v_add_co_u32_e32 v28, vcc, 0x40000, v22
	global_load_dwordx4 v[12:15], v[118:119], off offset:3072
	s_nop 0
	v_addc_co_u32_e32 v29, vcc, 0, v23, vcc
	v_add_co_u32_e32 v42, vcc, 0x80000, v22
	global_load_dwordx4 v[18:21], v[22:23], off
	s_nop 0
	global_load_dwordx4 v[28:31], v[28:29], off
	v_addc_co_u32_e32 v43, vcc, 0, v23, vcc
	v_add_co_u32_e32 v122, vcc, 0xc0000, v22
	s_nop 1
	v_addc_co_u32_e32 v123, vcc, 0, v23, vcc
	global_load_dwordx4 v[130:133], v[42:43], off
	global_load_dwordx4 v[134:137], v[122:123], off
	v_add_co_u32_e32 v42, vcc, 0x100000, v22
	s_nop 0
	s_nop 1
	v_addc_co_u32_e32 v43, vcc, 0, v23, vcc
	v_add_co_u32_e32 v122, vcc, 0x140000, v22
	s_nop 1
	v_addc_co_u32_e32 v123, vcc, 0, v23, vcc
	global_load_dwordx4 v[138:141], v[42:43], off
	global_load_dwordx4 v[142:145], v[122:123], off
	v_add_co_u32_e32 v42, vcc, 0x180000, v22
	s_nop 0
	s_nop 1
	v_addc_co_u32_e32 v43, vcc, 0, v23, vcc
	v_add_co_u32_e32 v22, vcc, 0x1c0000, v22
	global_load_dwordx4 v[146:149], v[42:43], off
	s_nop 0
	v_addc_co_u32_e32 v23, vcc, 0, v23, vcc
	global_load_dwordx4 v[150:153], v[22:23], off
	s_waitcnt vmcnt(7)
	v_pk_fma_f32 v[14:15], v[14:15], s[2:3], v[20:21] op_sel_hi:[1,0,1]
	v_pk_fma_f32 v[12:13], v[12:13], s[2:3], v[18:19] op_sel_hi:[1,0,1]
	s_waitcnt vmcnt(6)
	v_pk_add_f32 v[14:15], v[14:15], v[30:31]
	v_pk_add_f32 v[12:13], v[12:13], v[28:29]
	s_waitcnt vmcnt(5)
	v_pk_add_f32 v[14:15], v[14:15], v[132:133]
	v_pk_add_f32 v[12:13], v[12:13], v[130:131]
	s_waitcnt vmcnt(4)
	v_pk_add_f32 v[14:15], v[14:15], v[136:137]
	v_pk_add_f32 v[12:13], v[12:13], v[134:135]
	s_waitcnt vmcnt(3)
	v_pk_add_f32 v[14:15], v[14:15], v[140:141]
	v_pk_add_f32 v[12:13], v[12:13], v[138:139]
	s_waitcnt vmcnt(2)
	v_pk_add_f32 v[14:15], v[14:15], v[144:145]
	v_pk_add_f32 v[12:13], v[12:13], v[142:143]
	s_waitcnt vmcnt(1)
	v_pk_add_f32 v[14:15], v[14:15], v[148:149]
	v_pk_add_f32 v[12:13], v[12:13], v[146:147]
	s_waitcnt vmcnt(0)
	v_pk_add_f32 v[14:15], v[14:15], v[152:153]
	v_pk_add_f32 v[12:13], v[12:13], v[150:151]

; __device__ __forceinline__ void ln_load_row(const Params& p, const float* src, int which, int r, int lane, f32x4 (&x)[8]) {
;     ...
;     const int wg = gid * 64 + k * gsz + (pm - fm), off = wg % 36, xcd = wg / 36;
;     if (off >= 32) {
;       const int j = (off - 32) * 8 + xcd;
;       f32x4 v = *(const f32x4*)(rs + 256 * k + 4 * lane) * ALPHA;
;       const float* pp = part + (size_t)j * 8 * 65536 + (r & 255) * 256 + 4 * lane;
;       f32x4 t[8];
; #pragma unroll
;       for (int q = 0; q < 8; ++q) t[q] = *(const f32x4*)(pp + (size_t)q * 65536);
; #pragma unroll
;       for (int q = 0; q < 8; ++q) v += t[q];
;       x[k] = v;
.LBB0_143:
	s_andn2_saveexec_b64 s[38:39], s[38:39]
	s_cbranch_execz .LBB0_145
	s_waitcnt vmcnt(0)
	v_lshlrev_b32_e32 v16, 3, v22
	s_movk_i32 s29, 0xff00
	v_add3_u32 v22, v21, v16, s29
	v_ashrrev_i32_e32 v23, 31, v22
	v_add_co_u32_e32 v16, vcc, 0x1000, v118
	v_lshlrev_b64 v[22:23], 21, v[22:23]
	s_nop 0
	v_addc_co_u32_e32 v17, vcc, 0, v119, vcc
	v_lshl_add_u64 v[22:23], v[120:121], 0, v[22:23]
	v_add_co_u32_e32 v42, vcc, 0x40000, v22
	global_load_dwordx4 v[16:19], v[16:17], off
	s_nop 0
	v_addc_co_u32_e32 v43, vcc, 0, v23, vcc
	global_load_dwordx4 v[28:31], v[22:23], off
	global_load_dwordx4 v[130:133], v[42:43], off
	v_add_co_u32_e32 v42, vcc, 0x80000, v22
	s_nop 1
	v_addc_co_u32_e32 v43, vcc, 0, v23, vcc
	v_add_co_u32_e32 v122, vcc, 0xc0000, v22
	s_nop 0
	s_nop 1
	v_addc_co_u32_e32 v123, vcc, 0, v23, vcc
	global_load_dwordx4 v[134:137], v[42:43], off
	global_load_dwordx4 v[138:141], v[122:123], off
	v_add_co_u32_e32 v42, vcc, 0x100000, v22
	s_nop 1
	v_addc_co_u32_e32 v43, vcc, 0, v23, vcc
	v_add_co_u32_e32 v122, vcc, 0x140000, v22
	s_nop 0
	s_nop 1
	v_addc_co_u32_e32 v123, vcc, 0, v23, vcc
	global_load_dwordx4 v[142:145], v[42:43], off
	global_load_dwordx4 v[146:149], v[122:123], off
	v_add_co_u32_e32 v42, vcc, 0x180000, v22
	s_nop 1
	v_addc_co_u32_e32 v43, vcc, 0, v23, vcc
	v_add_co_u32_e32 v22, vcc, 0x1c0000, v22
	global_load_dwordx4 v[150:153], v[42:43], off
	s_nop 0
	v_addc_co_u32_e32 v23, vcc, 0, v23, vcc
	global_load_dwordx4 v[154:157], v[22:23], off
	s_waitcnt vmcnt(7)
	v_pk_fma_f32 v[18:19], v[18:19], s[2:3], v[30:31] op_sel_hi:[1,0,1]
	v_pk_fma_f32 v[16:17], v[16:17], s[2:3], v[28:29] op_sel_hi:[1,0,1]
	s_waitcnt vmcnt(6)
	v_pk_add_f32 v[18:19], v[18:19], v[132:133]
	v_pk_add_f32 v[16:17], v[16:17], v[130:131]
	s_waitcnt vmcnt(5)
	v_pk_add_f32 v[18:19], v[18:19], v[136:137]
	v_pk_add_f32 v[16:17], v[16:17], v[134:135]
	s_waitcnt vmcnt(4)
	v_pk_add_f32 v[18:19], v[18:19], v[140:141]
	v_pk_add_f32 v[16:17], v[16:17], v[138:139]
	s_waitcnt vmcnt(3)
	v_pk_add_f32 v[18:19], v[18:19], v[144:145]
	v_pk_add_f32 v[16:17], v[16:17], v[142:143]
	s_waitcnt vmcnt(2)
	v_pk_add_f32 v[18:19], v[18:19], v[148:149]
	v_pk_add_f32 v[16:17], v[16:17], v[146:147]
	s_waitcnt vmcnt(1)
	v_pk_add_f32 v[18:19], v[18:19], v[152:153]
	v_pk_add_f32 v[16:17], v[16:17], v[150:151]
	s_waitcnt vmcnt(0)
	v_pk_add_f32 v[18:19], v[18:19], v[156:157]
	v_pk_add_f32 v[16:17], v[16:17], v[154:155]

; __device__ __forceinline__ void ln_load_row(const Params& p, const float* src, int which, int r, int lane, f32x4 (&x)[8]) {
;     ...
;     const int wg = gid * 64 + k * gsz + (pm - fm), off = wg % 36, xcd = wg / 36;
;     if (off >= 32) {
;       const int j = (off - 32) * 8 + xcd;
;       f32x4 v = *(const f32x4*)(rs + 256 * k + 4 * lane) * ALPHA;
;       const float* pp = part + (size_t)j * 8 * 65536 + (r & 255) * 256 + 4 * lane;
;       f32x4 t[8];
; #pragma unroll
;       for (int q = 0; q < 8; ++q) t[q] = *(const f32x4*)(pp + (size_t)q * 65536);
; #pragma unroll
;       for (int q = 0; q < 8; ++q) v += t[q];
;       x[k] = v;
.LBB0_147:
	s_andn2_saveexec_b64 s[38:39], s[38:39]
	s_cbranch_execz .LBB0_149
	s_waitcnt vmcnt(0)
	v_lshlrev_b32_e32 v20, 3, v30
	s_movk_i32 s29, 0xff00
	v_add3_u32 v30, v29, v20, s29
	v_ashrrev_i32_e32 v31, 31, v30
	v_add_co_u32_e32 v20, vcc, 0x1000, v118
	v_lshlrev_b64 v[30:31], 21, v[30:31]
	s_nop 0
	v_addc_co_u32_e32 v21, vcc, 0, v119, vcc
	v_lshl_add_u64 v[30:31], v[120:121], 0, v[30:31]
	v_add_co_u32_e32 v42, vcc, 0x40000, v30
	global_load_dwordx4 v[20:23], v[20:21], off offset:1024
	s_nop 0
	v_addc_co_u32_e32 v43, vcc, 0, v31, vcc
	global_load_dwordx4 v[130:133], v[30:31], off
	global_load_dwordx4 v[134:137], v[42:43], off
	v_add_co_u32_e32 v42, vcc, 0x80000, v30
	s_nop 1
	v_addc_co_u32_e32 v43, vcc, 0, v31, vcc
	v_add_co_u32_e32 v122, vcc, 0xc0000, v30
	s_nop 0
	s_nop 1
	v_addc_co_u32_e32 v123, vcc, 0, v31, vcc
	global_load_dwordx4 v[138:141], v[42:43], off
	global_load_dwordx4 v[142:145], v[122:123], off
	v_add_co_u32_e32 v42, vcc, 0x100000, v30
	s_nop 1
	v_addc_co_u32_e32 v43, vcc, 0, v31, vcc
	v_add_co_u32_e32 v122, vcc, 0x140000, v30
	s_nop 0
	s_nop 1
	v_addc_co_u32_e32 v123, vcc, 0, v31, vcc
	global_load_dwordx4 v[146:149], v[42:43], off
	global_load_dwordx4 v[150:153], v[122:123], off
	v_add_co_u32_e32 v42, vcc, 0x180000, v30
	s_nop 1
	v_addc_co_u32_e32 v43, vcc, 0, v31, vcc
	v_add_co_u32_e32 v30, vcc, 0x1c0000, v30
	global_load_dwordx4 v[154:157], v[42:43], off
	s_nop 0
	v_addc_co_u32_e32 v31, vcc, 0, v31, vcc
	global_load_dwordx4 v[158:161], v[30:31], off
	s_waitcnt vmcnt(7)
	v_pk_fma_f32 v[22:23], v[22:23], s[2:3], v[132:133] op_sel_hi:[1,0,1]
	v_pk_fma_f32 v[20:21], v[20:21], s[2:3], v[130:131] op_sel_hi:[1,0,1]
	s_waitcnt vmcnt(6)
	v_pk_add_f32 v[22:23], v[22:23], v[136:137]
	v_pk_add_f32 v[20:21], v[20:21], v[134:135]
	s_waitcnt vmcnt(5)
	v_pk_add_f32 v[22:23], v[22:23], v[140:141]
	v_pk_add_f32 v[20:21], v[20:21], v[138:139]
	s_waitcnt vmcnt(4)
	v_pk_add_f32 v[22:23], v[22:23], v[144:145]
	v_pk_add_f32 v[20:21], v[20:21], v[142:143]
	s_waitcnt vmcnt(3)
	v_pk_add_f32 v[22:23], v[22:23], v[148:149]
	v_pk_add_f32 v[20:21], v[20:21], v[146:147]
	s_waitcnt vmcnt(2)
	v_pk_add_f32 v[22:23], v[22:23], v[152:153]
	v_pk_add_f32 v[20:21], v[20:21], v[150:151]
	s_waitcnt vmcnt(1)
	v_pk_add_f32 v[22:23], v[22:23], v[156:157]
	v_pk_add_f32 v[20:21], v[20:21], v[154:155]
	s_waitcnt vmcnt(0)
	v_pk_add_f32 v[22:23], v[22:23], v[160:161]
	v_pk_add_f32 v[20:21], v[20:21], v[158:159]

; __device__ __forceinline__ void ln_load_row(const Params& p, const float* src, int which, int r, int lane, f32x4 (&x)[8]) {
;     ...
;     const int wg = gid * 64 + k * gsz + (pm - fm), off = wg % 36, xcd = wg / 36;
;     if (off >= 32) {
;       const int j = (off - 32) * 8 + xcd;
;       f32x4 v = *(const f32x4*)(rs + 256 * k + 4 * lane) * ALPHA;
;       const float* pp = part + (size_t)j * 8 * 65536 + (r & 255) * 256 + 4 * lane;
;       f32x4 t[8];
; #pragma unroll
;       for (int q = 0; q < 8; ++q) t[q] = *(const f32x4*)(pp + (size_t)q * 65536);
; #pragma unroll
;       for (int q = 0; q < 8; ++q) v += t[q];
;       x[k] = v;
.LBB0_151:
	s_andn2_saveexec_b64 s[38:39], s[38:39]
	s_cbranch_execz .LBB0_153
	s_waitcnt vmcnt(0)
	v_lshlrev_b32_e32 v28, 3, v43
	s_movk_i32 s29, 0xff00
	v_add3_u32 v42, v42, v28, s29
	v_ashrrev_i32_e32 v43, 31, v42
	v_add_co_u32_e32 v28, vcc, 0x1000, v118
	v_lshlrev_b64 v[42:43], 21, v[42:43]
	s_nop 0
	v_addc_co_u32_e32 v29, vcc, 0, v119, vcc
	v_lshl_add_u64 v[42:43], v[120:121], 0, v[42:43]
	v_add_co_u32_e32 v122, vcc, 0x40000, v42
	global_load_dwordx4 v[28:31], v[28:29], off offset:2048
	s_nop 0
	v_addc_co_u32_e32 v123, vcc, 0, v43, vcc
	global_load_dwordx4 v[130:133], v[42:43], off
	global_load_dwordx4 v[134:137], v[122:123], off
	v_add_co_u32_e32 v122, vcc, 0x80000, v42
	s_nop 1
	v_addc_co_u32_e32 v123, vcc, 0, v43, vcc
	v_add_co_u32_e32 v142, vcc, 0xc0000, v42
	s_nop 0
	s_nop 1
	v_addc_co_u32_e32 v143, vcc, 0, v43, vcc
	global_load_dwordx4 v[138:141], v[122:123], off
	s_nop 0
	global_load_dwordx4 v[142:145], v[142:143], off
	v_add_co_u32_e32 v122, vcc, 0x100000, v42
	s_nop 1
	v_addc_co_u32_e32 v123, vcc, 0, v43, vcc
	v_add_co_u32_e32 v150, vcc, 0x140000, v42
	s_nop 0
	s_nop 1
	v_addc_co_u32_e32 v151, vcc, 0, v43, vcc
	global_load_dwordx4 v[146:149], v[122:123], off
	s_nop 0
	global_load_dwordx4 v[150:153], v[150:151], off
	v_add_co_u32_e32 v122, vcc, 0x180000, v42
	s_nop 1
	v_addc_co_u32_e32 v123, vcc, 0, v43, vcc
	v_add_co_u32_e32 v42, vcc, 0x1c0000, v42
	global_load_dwordx4 v[154:157], v[122:123], off
	s_nop 0
	v_addc_co_u32_e32 v43, vcc, 0, v43, vcc
	global_load_dwordx4 v[158:161], v[42:43], off
	s_waitcnt vmcnt(7)
	v_pk_fma_f32 v[30:31], v[30:31], s[2:3], v[132:133] op_sel_hi:[1,0,1]
	v_pk_fma_f32 v[28:29], v[28:29], s[2:3], v[130:131] op_sel_hi:[1,0,1]
	s_waitcnt vmcnt(6)
	v_pk_add_f32 v[30:31], v[30:31], v[136:137]
	v_pk_add_f32 v[28:29], v[28:29], v[134:135]
	s_waitcnt vmcnt(5)
	v_pk_add_f32 v[30:31], v[30:31], v[140:141]
	v_pk_add_f32 v[28:29], v[28:29], v[138:139]
	s_waitcnt vmcnt(4)
	v_pk_add_f32 v[30:31], v[30:31], v[144:145]
	v_pk_add_f32 v[28:29], v[28:29], v[142:143]
	s_waitcnt vmcnt(3)
	v_pk_add_f32 v[30:31], v[30:31], v[148:149]
	v_pk_add_f32 v[28:29], v[28:29], v[146:147]
	s_waitcnt vmcnt(2)
	v_pk_add_f32 v[30:31], v[30:31], v[152:153]
	v_pk_add_f32 v[28:29], v[28:29], v[150:151]
	s_waitcnt vmcnt(1)
	v_pk_add_f32 v[30:31], v[30:31], v[156:157]
	v_pk_add_f32 v[28:29], v[28:29], v[154:155]
	s_waitcnt vmcnt(0)
	v_pk_add_f32 v[30:31], v[30:31], v[160:161]
	v_pk_add_f32 v[28:29], v[28:29], v[158:159]

; __device__ __forceinline__ void ln_load_row(const Params& p, const float* src, int which, int r, int lane, f32x4 (&x)[8]) {
;     ...
;     const int wg = gid * 64 + k * gsz + (pm - fm), off = wg % 36, xcd = wg / 36;
;     if (off >= 32) {
;       const int j = (off - 32) * 8 + xcd;
;       f32x4 v = *(const f32x4*)(rs + 256 * k + 4 * lane) * ALPHA;
;       const float* pp = part + (size_t)j * 8 * 65536 + (r & 255) * 256 + 4 * lane;
;       f32x4 t[8];
; #pragma unroll
;       for (int q = 0; q < 8; ++q) t[q] = *(const f32x4*)(pp + (size_t)q * 65536);
; #pragma unroll
;       for (int q = 0; q < 8; ++q) v += t[q];
;       x[k] = v;
.LBB0_155:
	s_andn2_saveexec_b64 s[38:39], s[38:39]
	s_cbranch_execz .LBB0_157
	s_waitcnt vmcnt(0)
	v_lshlrev_b32_e32 v40, 3, v103
	s_movk_i32 s29, 0xff00
	v_add3_u32 v116, v67, v40, s29
	v_ashrrev_i32_e32 v117, 31, v116
	v_add_co_u32_e32 v40, vcc, 0x1000, v118
	v_lshlrev_b64 v[116:117], 21, v[116:117]
	s_nop 0
	v_addc_co_u32_e32 v41, vcc, 0, v119, vcc
	v_lshl_add_u64 v[150:151], v[120:121], 0, v[116:117]
	v_add_co_u32_e32 v120, vcc, 0x40000, v150
	global_load_dwordx4 v[40:43], v[40:41], off offset:3072
	s_nop 0
	v_addc_co_u32_e32 v121, vcc, 0, v151, vcc
	v_add_co_u32_e32 v130, vcc, 0x80000, v150
	global_load_dwordx4 v[116:119], v[150:151], off
	s_nop 0
	global_load_dwordx4 v[120:123], v[120:121], off
	v_addc_co_u32_e32 v131, vcc, 0, v151, vcc
	v_add_co_u32_e32 v134, vcc, 0xc0000, v150
	s_nop 1
	v_addc_co_u32_e32 v135, vcc, 0, v151, vcc
	v_add_co_u32_e32 v138, vcc, 0x100000, v150
	global_load_dwordx4 v[130:133], v[130:131], off
	s_nop 0
	global_load_dwordx4 v[134:137], v[134:135], off
	v_addc_co_u32_e32 v139, vcc, 0, v151, vcc
	v_add_co_u32_e32 v142, vcc, 0x140000, v150
	s_nop 0
	s_nop 1
	v_addc_co_u32_e32 v143, vcc, 0, v151, vcc
	v_add_co_u32_e32 v146, vcc, 0x180000, v150
	global_load_dwordx4 v[138:141], v[138:139], off
	s_nop 0
	global_load_dwordx4 v[142:145], v[142:143], off
	v_addc_co_u32_e32 v147, vcc, 0, v151, vcc
	v_add_co_u32_e32 v150, vcc, 0x1c0000, v150
	global_load_dwordx4 v[146:149], v[146:147], off
	s_nop 0
	v_addc_co_u32_e32 v151, vcc, 0, v151, vcc
	global_load_dwordx4 v[150:153], v[150:151], off
	s_waitcnt vmcnt(7)
	v_pk_fma_f32 v[42:43], v[42:43], s[2:3], v[118:119] op_sel_hi:[1,0,1]
	v_pk_fma_f32 v[40:41], v[40:41], s[2:3], v[116:117] op_sel_hi:[1,0,1]
	s_waitcnt vmcnt(6)
	v_pk_add_f32 v[42:43], v[42:43], v[122:123]
	v_pk_add_f32 v[40:41], v[40:41], v[120:121]
	s_waitcnt vmcnt(5)
	v_pk_add_f32 v[42:43], v[42:43], v[132:133]
	v_pk_add_f32 v[40:41], v[40:41], v[130:131]
	s_waitcnt vmcnt(4)
	v_pk_add_f32 v[42:43], v[42:43], v[136:137]
	v_pk_add_f32 v[40:41], v[40:41], v[134:135]
	s_waitcnt vmcnt(3)
	v_pk_add_f32 v[42:43], v[42:43], v[140:141]
	v_pk_add_f32 v[40:41], v[40:41], v[138:139]
	s_waitcnt vmcnt(2)
	v_pk_add_f32 v[42:43], v[42:43], v[144:145]
	v_pk_add_f32 v[40:41], v[40:41], v[142:143]
	s_waitcnt vmcnt(1)
	v_pk_add_f32 v[42:43], v[42:43], v[148:149]
	v_pk_add_f32 v[40:41], v[40:41], v[146:147]
	s_waitcnt vmcnt(0)
	v_pk_add_f32 v[42:43], v[42:43], v[152:153]
	v_pk_add_f32 v[40:41], v[40:41], v[150:151]

; __device__ __forceinline__ u32x2 pack4(f32x4 v) { u32x2 r; r[0] = cvt_pk(v[0], v[1]); r[1] = cvt_pk(v[2], v[3]); return r; }
; __device__ __forceinline__ float siluf_(float x) { return x * sigmoidf_(x); }
; __device__ __forceinline__ void ffn_split_reduce(const Params& p) {
;     ...
;   for (int wk = blockIdx.x; wk < 384; wk += gridDim.x) {
;     const int t = wk >> 3, sl = wk & 7;
;     int pm, pn; static_tile(36, 44, 1536 + t, pm, pn);
;     const float* pt = (const float*)(p.ws + WS_PART) + (size_t)t * 4 * 65536 + sl * 8192;
; #pragma unroll
;     for (int it = 0; it < 2; ++it) {
;       const int idx = it * 512 + tid, rl = idx >> 5, g5 = idx & 31;
;       const int bj = g5 >> 4, wc = (g5 >> 2) & 3, lg = g5 & 3;
;       const int cl = 128 * bj + 32 * wc + 4 * lg;
;       f32x4 tg[4], tu[4];
; #pragma unroll
;       for (int q = 0; q < 4; ++q) { tg[q] = *(const f32x4*)(pt + (size_t)q * 65536 + rl * 256 + cl); tu[q] = *(const f32x4*)(pt + (size_t)q * 65536 + rl * 256 + cl + 16); }
;       const f32x4 g = tg[0] + tg[1] + tg[2] + tg[3], uu = tu[0] + tu[1] + tu[2] + tu[3];
;       f32x4 v; v[0] = siluf_(g[0]) * uu[0]; v[1] = siluf_(g[1]) * uu[1]; v[2] = siluf_(g[2]) * uu[2]; v[3] = siluf_(g[3]) * uu[3];
;       *(u32x2*)(act + (size_t)(pm * 256 + sl * 32 + rl) * DFF + pn * 128 + 64 * bj + 16 * wc + 4 * lg) = pack4(v);
;     }
.LBB0_1487:
	s_ashr_i32 s36, s29, 3
	s_add_i32 s34, s36, 0x600
	s_lshr_b32 s35, s34, 29
	s_add_i32 s35, s34, s35
	s_ashr_i32 s37, s35, 3
	s_and_b32 s35, s35, -8
	s_and_b32 s38, s29, 7
	s_sub_i32 s34, s34, s35
	s_cmp_lt_i32 s34, 0
	s_cselect_b32 s35, s71, 0xc6
	s_mul_i32 s34, s35, s34
	s_add_i32 s34, s34, s37
	s_mul_hi_i32 s35, s34, 0x2e8ba2e9
	s_lshr_b32 s37, s35, 31
	s_ashr_i32 s35, s35, 6
	s_add_i32 s35, s35, s37
	s_lshl_b32 s37, s35, 3
	s_sub_i32 s39, 36, s37
	s_min_u32 s39, s39, 8
	s_mulk_i32 s35, 0x160
	s_sub_i32 s40, s34, s35
	v_cvt_f32_ubyte0_e32 v7, s39
	v_cvt_f32_i32_e32 v6, s40
	v_rcp_iflag_f32_e32 v8, v7
	s_ashr_i32 s34, s40, 30
	s_or_b32 s41, s34, 1
	v_mul_f32_e32 v8, v6, v8
	v_trunc_f32_e32 v8, v8
	v_fma_f32 v6, -v8, v7, v6
	v_cvt_i32_f32_e32 v8, v8
	v_cmp_ge_f32_e64 s[34:35], |v6|, v7
	s_and_b64 s[34:35], s[34:35], exec
	s_cselect_b32 s34, s41, 0
	v_readfirstlane_b32 s35, v8
	s_add_i32 s34, s35, s34
	s_sext_i32_i16 s41, s34
	s_mul_i32 s34, s34, s39
	s_sub_i32 s34, s40, s34
	s_sext_i32_i16 s34, s34
	s_add_i32 s39, s37, s34
	s_ashr_i32 s37, s36, 31
	s_lshl_b64 s[34:35], s[36:37], 20
	s_add_u32 s34, s72, s34
	s_addc_u32 s35, s73, s35
	s_lshl_b32 s36, s38, 15
	s_add_u32 s34, s34, s36
	s_addc_u32 s35, s35, 0
	v_lshl_add_u64 v[8:9], s[34:35], 0, v[64:65]
	v_lshl_add_u64 v[36:37], v[2:3], 2, v[8:9]
	v_add_co_u32_e32 v24, vcc, s74, v36
	global_load_dwordx4 v[12:15], v[36:37], off
	global_load_dwordx4 v[16:19], v[36:37], off offset:64
	v_addc_co_u32_e32 v25, vcc, 0, v37, vcc
	v_add_co_u32_e32 v32, vcc, s42, v36
	global_load_dwordx4 v[20:23], v[24:25], off
	s_nop 0
	global_load_dwordx4 v[24:27], v[24:25], off offset:64
	v_addc_co_u32_e32 v33, vcc, 0, v37, vcc
	v_add_co_u32_e32 v40, vcc, s43, v36
	global_load_dwordx4 v[28:31], v[32:33], off
	s_nop 0
	global_load_dwordx4 v[32:35], v[32:33], off offset:64
	v_addc_co_u32_e32 v41, vcc, 0, v37, vcc
	global_load_dwordx4 v[36:39], v[40:41], off
	s_nop 0
	global_load_dwordx4 v[40:43], v[40:41], off offset:64
	s_lshl_b32 s34, s39, 8
	s_lshl_b32 s35, s38, 5
	s_lshl_b32 s36, s41, 7
	v_lshl_add_u64 v[8:9], v[4:5], 2, v[8:9]
	global_load_dwordx4 v[100:103], v[8:9], off
	global_load_dwordx4 v[104:107], v[8:9], off offset:64
	v_add_co_u32_e32 v132, vcc, s74, v8
	s_nop 1
	v_addc_co_u32_e32 v133, vcc, 0, v9, vcc
	global_load_dwordx4 v[108:111], v[132:133], off
	global_load_dwordx4 v[112:115], v[132:133], off offset:64
	v_add_co_u32_e32 v134, vcc, s42, v8
	s_nop 1
	v_addc_co_u32_e32 v135, vcc, 0, v9, vcc
	global_load_dwordx4 v[116:119], v[134:135], off
	global_load_dwordx4 v[120:123], v[134:135], off offset:64
	v_add_co_u32_e32 v136, vcc, s43, v8
	s_nop 1
	v_addc_co_u32_e32 v137, vcc, 0, v9, vcc
	global_load_dwordx4 v[124:127], v[136:137], off
	global_load_dwordx4 v[128:131], v[136:137], off offset:64
	s_or_b32 s34, s34, s35
	s_ashr_i32 s37, s36, 31
	v_lshl_add_u64 v[6:7], s[36:37], 1, v[0:1]
	s_waitcnt vmcnt(13)
	v_pk_add_f32 v[12:13], v[12:13], v[20:21]
	v_pk_add_f32 v[14:15], v[14:15], v[22:23]
	s_waitcnt vmcnt(12)
	v_pk_add_f32 v[16:17], v[16:17], v[24:25]
	v_pk_add_f32 v[18:19], v[18:19], v[26:27]
	v_add_co_u32_e32 v24, vcc, s74, v8
	s_waitcnt vmcnt(11)
	v_pk_add_f32 v[12:13], v[12:13], v[28:29]
	v_pk_add_f32 v[14:15], v[14:15], v[30:31]
	s_waitcnt vmcnt(9)
	v_pk_add_f32 v[12:13], v[12:13], v[36:37]
	v_pk_add_f32 v[16:17], v[16:17], v[32:33]
	v_mul_f32_e32 v20, 0xbfb8aa3b, v12
	v_mul_f32_e32 v21, 0xbfb8aa3b, v13
	v_exp_f32_e32 v20, v20
	v_exp_f32_e32 v21, v21
	v_pk_add_f32 v[14:15], v[14:15], v[38:39]
	s_waitcnt vmcnt(8)
	v_pk_add_f32 v[16:17], v[16:17], v[40:41]
	v_add_f32_e32 v20, 1.0, v20
	v_add_f32_e32 v21, 1.0, v21
	v_rcp_f32_e32 v20, v20
	v_rcp_f32_e32 v21, v21
	v_pk_add_f32 v[18:19], v[18:19], v[34:35]
	v_addc_co_u32_e32 v25, vcc, 0, v9, vcc
	v_pk_mul_f32 v[12:13], v[12:13], v[20:21]
	v_pk_add_f32 v[18:19], v[18:19], v[42:43]
	v_pk_mul_f32 v[12:13], v[16:17], v[12:13]
	v_mul_f32_e32 v16, 0xbfb8aa3b, v14
	v_mul_f32_e32 v17, 0xbfb8aa3b, v15
	v_exp_f32_e32 v16, v16
	v_exp_f32_e32 v17, v17
	v_cvt_pk_bf16_f32 v12, v12, v13
	v_add_co_u32_e32 v32, vcc, s42, v8
	v_add_f32_e32 v16, 1.0, v16
	v_add_f32_e32 v17, 1.0, v17
	v_rcp_f32_e32 v16, v16
	v_rcp_f32_e32 v17, v17
	v_addc_co_u32_e32 v33, vcc, 0, v9, vcc
	v_pk_mul_f32 v[14:15], v[14:15], v[16:17]
	s_nop 0
	v_pk_mul_f32 v[14:15], v[18:19], v[14:15]
	s_nop 0
	v_cvt_pk_bf16_f32 v13, v14, v15
	v_add_u32_e32 v14, s34, v10
	v_mad_i64_i32 v[14:15], s[36:37], v14, s44, v[6:7]
	global_store_dwordx2 v[14:15], v[12:13], off
	s_nop 0
	s_nop 0
	v_add_co_u32_e32 v8, vcc, s43, v8
	s_nop 0
	v_addc_co_u32_e32 v9, vcc, 0, v9, vcc
	s_waitcnt vmcnt(1)
	v_pk_add_f32 v[100:101], v[100:101], v[108:109]
	v_pk_add_f32 v[8:9], v[102:103], v[110:111]
	v_pk_add_f32 v[102:103], v[106:107], v[114:115]
	v_pk_add_f32 v[100:101], v[100:101], v[116:117]
	v_pk_add_f32 v[104:105], v[104:105], v[112:113]
	v_pk_add_f32 v[8:9], v[8:9], v[118:119]
	v_pk_add_f32 v[100:101], v[100:101], v[124:125]
	v_pk_add_f32 v[104:105], v[104:105], v[120:121]
	v_mul_f32_e32 v106, 0xbfb8aa3b, v100
	v_mul_f32_e32 v107, 0xbfb8aa3b, v101
	v_exp_f32_e32 v106, v106
	v_exp_f32_e32 v107, v107
	v_pk_add_f32 v[8:9], v[8:9], v[126:127]
	v_pk_add_f32 v[104:105], v[104:105], v[128:129]
	v_add_f32_e32 v106, 1.0, v106
	v_add_f32_e32 v107, 1.0, v107
	v_rcp_f32_e32 v106, v106
	v_rcp_f32_e32 v107, v107
	v_pk_add_f32 v[102:103], v[102:103], v[122:123]
	v_pk_mul_f32 v[100:101], v[100:101], v[106:107]
	s_nop 0
	v_pk_mul_f32 v[100:101], v[104:105], v[100:101]
	v_mul_f32_e32 v104, 0xbfb8aa3b, v8
	v_mul_f32_e32 v105, 0xbfb8aa3b, v9
	v_exp_f32_e32 v104, v104
	v_exp_f32_e32 v105, v105
	v_pk_add_f32 v[102:103], v[102:103], v[130:131]
	v_cvt_pk_bf16_f32 v100, v100, v101
	v_add_f32_e32 v104, 1.0, v104
	v_add_f32_e32 v105, 1.0, v105
	v_rcp_f32_e32 v104, v104
	v_rcp_f32_e32 v105, v105
	s_nop 0
	v_pk_mul_f32 v[8:9], v[8:9], v[104:105]
	s_nop 0
	v_pk_mul_f32 v[8:9], v[102:103], v[8:9]
	s_nop 0
	v_cvt_pk_bf16_f32 v101, v8, v9
	v_add_u32_e32 v8, s34, v11
	v_mad_i64_i32 v[6:7], s[34:35], v8, s44, v[6:7]
	s_add_i32 s34, s29, 0x100
	s_cmpk_gt_i32 s29, 0x7f
	s_mov_b32 s29, s34
	global_store_dwordx2 v[6:7], v[100:101], off
	s_cbranch_scc0 .LBB0_1487

; __device__ __forceinline__ void ln_load_row(const Params& p, const float* src, int which, int r, int lane, f32x4 (&x)[8]) {
;   const float* part = (const float*)(p.ws + WS_PART);
;   const float* s = src + (size_t)r * 2048;
;   const float* rs = which == 0 ? (r < TOKP ? p.in[0] + (size_t)r * 2048 : p.in[1] + (size_t)(r - TOKP) * 2048) : (const float*)(p.ws + WS_X1) + (size_t)r * 2048;
;   const int pm = r >> 8, gid = pm >> 3, fm = gid * 8, gsz = (36 - fm) < 8 ? (36 - fm) : 8;
; #pragma unroll
;   for (int k = 0; k < 8; ++k) {
;     const int wg = gid * 64 + k * gsz + (pm - fm), off = wg % 36, xcd = wg / 36;
;     if (off >= 32) {
;       const int j = (off - 32) * 8 + xcd;
;       f32x4 v = *(const f32x4*)(rs + 256 * k + 4 * lane) * ALPHA;
;       const float* pp = part + (size_t)j * 8 * 65536 + (r & 255) * 256 + 4 * lane;
;       f32x4 t[8];
; #pragma unroll
;       for (int q = 0; q < 8; ++q) t[q] = *(const f32x4*)(pp + (size_t)q * 65536);
; #pragma unroll
;       for (int q = 0; q < 8; ++q) v += t[q];
;       x[k] = v;
.LBB0_1497:
	s_or_saveexec_b64 s[36:37], s[36:37]
	v_and_b32_e32 v36, 0xff00, v126
	v_lshlrev_b32_e32 v64, 2, v36
	v_lshl_add_u64 v[112:113], v[92:93], 0, v[64:65]
	s_xor_b64 exec, exec, s[36:37]
	s_cbranch_execz .LBB0_1499
	s_waitcnt vmcnt(0)
	v_lshlrev_b32_e32 v20, 3, v31
	s_movk_i32 s29, 0xff00
	v_add3_u32 v30, v30, v20, s29
	v_ashrrev_i32_e32 v31, 31, v30
	v_add_co_u32_e32 v20, vcc, 0x109000, v110
	v_lshlrev_b64 v[30:31], 21, v[30:31]
	s_nop 0
	v_addc_co_u32_e32 v21, vcc, 0, v111, vcc
	v_lshl_add_u64 v[30:31], v[112:113], 0, v[30:31]
	v_add_co_u32_e32 v44, vcc, 0x40000, v30
	global_load_dwordx4 v[20:23], v[20:21], off
	s_nop 0
	v_addc_co_u32_e32 v45, vcc, 0, v31, vcc
	v_add_co_u32_e32 v48, vcc, 0x80000, v30
	global_load_dwordx4 v[36:39], v[30:31], off
	s_nop 0
	global_load_dwordx4 v[44:47], v[44:45], off
	v_addc_co_u32_e32 v49, vcc, 0, v31, vcc
	v_add_co_u32_e32 v52, vcc, 0xc0000, v30
	s_nop 1
	v_addc_co_u32_e32 v53, vcc, 0, v31, vcc
	v_add_co_u32_e32 v56, vcc, 0x100000, v30
	global_load_dwordx4 v[48:51], v[48:49], off
	s_nop 0
	global_load_dwordx4 v[52:55], v[52:53], off
	v_addc_co_u32_e32 v57, vcc, 0, v31, vcc
	v_add_co_u32_e32 v60, vcc, 0x140000, v30
	s_nop 0
	s_nop 1
	v_addc_co_u32_e32 v61, vcc, 0, v31, vcc
	v_add_co_u32_e32 v114, vcc, 0x180000, v30
	global_load_dwordx4 v[56:59], v[56:57], off
	s_nop 0
	global_load_dwordx4 v[60:63], v[60:61], off
	v_addc_co_u32_e32 v115, vcc, 0, v31, vcc
	v_add_co_u32_e32 v30, vcc, 0x1c0000, v30
	global_load_dwordx4 v[114:117], v[114:115], off
	s_nop 0
	v_addc_co_u32_e32 v31, vcc, 0, v31, vcc
	global_load_dwordx4 v[128:131], v[30:31], off
	s_waitcnt vmcnt(7)
	v_pk_fma_f32 v[22:23], v[22:23], s[2:3], v[38:39] op_sel_hi:[1,0,1]
	v_pk_fma_f32 v[20:21], v[20:21], s[2:3], v[36:37] op_sel_hi:[1,0,1]
	s_waitcnt vmcnt(6)
	v_pk_add_f32 v[22:23], v[22:23], v[46:47]
	v_pk_add_f32 v[20:21], v[20:21], v[44:45]
	s_waitcnt vmcnt(5)
	v_pk_add_f32 v[22:23], v[22:23], v[50:51]
	v_pk_add_f32 v[20:21], v[20:21], v[48:49]
	s_waitcnt vmcnt(4)
	v_pk_add_f32 v[22:23], v[22:23], v[54:55]
	v_pk_add_f32 v[20:21], v[20:21], v[52:53]
	s_waitcnt vmcnt(3)
	v_pk_add_f32 v[22:23], v[22:23], v[58:59]
	v_pk_add_f32 v[20:21], v[20:21], v[56:57]
	s_waitcnt vmcnt(2)
	v_pk_add_f32 v[22:23], v[22:23], v[62:63]
	v_pk_add_f32 v[20:21], v[20:21], v[60:61]
	s_waitcnt vmcnt(1)
	v_pk_add_f32 v[22:23], v[22:23], v[116:117]
	v_pk_add_f32 v[20:21], v[20:21], v[114:115]
	s_waitcnt vmcnt(0)
	v_pk_add_f32 v[22:23], v[22:23], v[130:131]
	v_pk_add_f32 v[20:21], v[20:21], v[128:129]

; __device__ __forceinline__ void ln_load_row(const Params& p, const float* src, int which, int r, int lane, f32x4 (&x)[8]) {
;     ...
;     const int wg = gid * 64 + k * gsz + (pm - fm), off = wg % 36, xcd = wg / 36;
;     if (off >= 32) {
;       const int j = (off - 32) * 8 + xcd;
;       f32x4 v = *(const f32x4*)(rs + 256 * k + 4 * lane) * ALPHA;
;       const float* pp = part + (size_t)j * 8 * 65536 + (r & 255) * 256 + 4 * lane;
;       f32x4 t[8];
; #pragma unroll
;       for (int q = 0; q < 8; ++q) t[q] = *(const f32x4*)(pp + (size_t)q * 65536);
; #pragma unroll
;       for (int q = 0; q < 8; ++q) v += t[q];
;       x[k] = v;
.LBB0_1501:
	s_andn2_saveexec_b64 s[36:37], s[36:37]
	s_cbranch_execz .LBB0_1503
	s_waitcnt vmcnt(0)
	v_lshlrev_b32_e32 v28, 3, v38
	s_movk_i32 s29, 0xff00
	v_add3_u32 v38, v37, v28, s29
	v_ashrrev_i32_e32 v39, 31, v38
	v_add_co_u32_e32 v28, vcc, 0x109000, v110
	v_lshlrev_b64 v[38:39], 21, v[38:39]
	s_nop 0
	v_addc_co_u32_e32 v29, vcc, 0, v111, vcc
	v_lshl_add_u64 v[38:39], v[112:113], 0, v[38:39]
	v_add_co_u32_e32 v48, vcc, 0x40000, v38
	global_load_dwordx4 v[28:31], v[28:29], off offset:1024
	s_nop 0
	v_addc_co_u32_e32 v49, vcc, 0, v39, vcc
	v_add_co_u32_e32 v52, vcc, 0x80000, v38
	global_load_dwordx4 v[44:47], v[38:39], off
	s_nop 0
	global_load_dwordx4 v[48:51], v[48:49], off
	v_addc_co_u32_e32 v53, vcc, 0, v39, vcc
	v_add_co_u32_e32 v56, vcc, 0xc0000, v38
	s_nop 1
	v_addc_co_u32_e32 v57, vcc, 0, v39, vcc
	v_add_co_u32_e32 v62, vcc, 0x100000, v38
	global_load_dwordx4 v[52:55], v[52:53], off
	s_nop 0
	global_load_dwordx4 v[56:59], v[56:57], off
	v_addc_co_u32_e32 v63, vcc, 0, v39, vcc
	v_add_co_u32_e32 v118, vcc, 0x140000, v38
	s_nop 0
	s_nop 1
	v_addc_co_u32_e32 v119, vcc, 0, v39, vcc
	global_load_dwordx4 v[114:117], v[62:63], off
	global_load_dwordx4 v[128:131], v[118:119], off
	v_add_co_u32_e32 v62, vcc, 0x180000, v38
	s_nop 0
	s_nop 1
	v_addc_co_u32_e32 v63, vcc, 0, v39, vcc
	v_add_co_u32_e32 v38, vcc, 0x1c0000, v38
	global_load_dwordx4 v[132:135], v[62:63], off
	s_nop 0
	v_addc_co_u32_e32 v39, vcc, 0, v39, vcc
	global_load_dwordx4 v[136:139], v[38:39], off
	s_waitcnt vmcnt(7)
	v_pk_fma_f32 v[30:31], v[30:31], s[2:3], v[46:47] op_sel_hi:[1,0,1]
	v_pk_fma_f32 v[28:29], v[28:29], s[2:3], v[44:45] op_sel_hi:[1,0,1]
	s_waitcnt vmcnt(6)
	v_pk_add_f32 v[30:31], v[30:31], v[50:51]
	v_pk_add_f32 v[28:29], v[28:29], v[48:49]
	s_waitcnt vmcnt(5)
	v_pk_add_f32 v[30:31], v[30:31], v[54:55]
	v_pk_add_f32 v[28:29], v[28:29], v[52:53]
	s_waitcnt vmcnt(4)
	v_pk_add_f32 v[30:31], v[30:31], v[58:59]
	v_pk_add_f32 v[28:29], v[28:29], v[56:57]
	s_waitcnt vmcnt(3)
	v_pk_add_f32 v[30:31], v[30:31], v[116:117]
	v_pk_add_f32 v[28:29], v[28:29], v[114:115]
	s_waitcnt vmcnt(2)
	v_pk_add_f32 v[30:31], v[30:31], v[130:131]
	v_pk_add_f32 v[28:29], v[28:29], v[128:129]
	s_waitcnt vmcnt(1)
	v_pk_add_f32 v[30:31], v[30:31], v[134:135]
	v_pk_add_f32 v[28:29], v[28:29], v[132:133]
	s_waitcnt vmcnt(0)
	v_pk_add_f32 v[30:31], v[30:31], v[138:139]
	v_pk_add_f32 v[28:29], v[28:29], v[136:137]

; __device__ __forceinline__ void ln_load_row(const Params& p, const float* src, int which, int r, int lane, f32x4 (&x)[8]) {
;     ...
;     const int wg = gid * 64 + k * gsz + (pm - fm), off = wg % 36, xcd = wg / 36;
;     if (off >= 32) {
;       const int j = (off - 32) * 8 + xcd;
;       f32x4 v = *(const f32x4*)(rs + 256 * k + 4 * lane) * ALPHA;
;       const float* pp = part + (size_t)j * 8 * 65536 + (r & 255) * 256 + 4 * lane;
;       f32x4 t[8];
; #pragma unroll
;       for (int q = 0; q < 8; ++q) t[q] = *(const f32x4*)(pp + (size_t)q * 65536);
; #pragma unroll
;       for (int q = 0; q < 8; ++q) v += t[q];
;       x[k] = v;
.LBB0_1505:
	s_andn2_saveexec_b64 s[36:37], s[36:37]
	s_cbranch_execz .LBB0_1507
	s_waitcnt vmcnt(0)
	v_lshlrev_b32_e32 v36, 3, v46
	s_movk_i32 s29, 0xff00
	v_add3_u32 v46, v45, v36, s29
	v_ashrrev_i32_e32 v47, 31, v46
	v_add_co_u32_e32 v36, vcc, 0x109000, v110
	v_lshlrev_b64 v[46:47], 21, v[46:47]
	s_nop 0
	v_addc_co_u32_e32 v37, vcc, 0, v111, vcc
	v_lshl_add_u64 v[58:59], v[112:113], 0, v[46:47]
	v_add_co_u32_e32 v50, vcc, 0x40000, v58
	global_load_dwordx4 v[36:39], v[36:37], off offset:2048
	s_nop 0
	v_addc_co_u32_e32 v51, vcc, 0, v59, vcc
	v_add_co_u32_e32 v54, vcc, 0x80000, v58
	global_load_dwordx4 v[46:49], v[58:59], off
	s_nop 0
	global_load_dwordx4 v[50:53], v[50:51], off
	v_addc_co_u32_e32 v55, vcc, 0, v59, vcc
	v_add_co_u32_e32 v62, vcc, 0xc0000, v58
	s_nop 1
	v_addc_co_u32_e32 v63, vcc, 0, v59, vcc
	global_load_dwordx4 v[54:57], v[54:55], off
	s_nop 0
	global_load_dwordx4 v[114:117], v[62:63], off
	v_add_co_u32_e32 v62, vcc, 0x100000, v58
	s_nop 0
	s_nop 1
	v_addc_co_u32_e32 v63, vcc, 0, v59, vcc
	v_add_co_u32_e32 v118, vcc, 0x140000, v58
	s_nop 0
	s_nop 1
	v_addc_co_u32_e32 v119, vcc, 0, v59, vcc
	global_load_dwordx4 v[128:131], v[62:63], off
	global_load_dwordx4 v[132:135], v[118:119], off
	v_add_co_u32_e32 v62, vcc, 0x180000, v58
	s_nop 0
	s_nop 1
	v_addc_co_u32_e32 v63, vcc, 0, v59, vcc
	v_add_co_u32_e32 v58, vcc, 0x1c0000, v58
	global_load_dwordx4 v[136:139], v[62:63], off
	s_nop 0
	v_addc_co_u32_e32 v59, vcc, 0, v59, vcc
	global_load_dwordx4 v[140:143], v[58:59], off
	s_waitcnt vmcnt(7)
	v_pk_fma_f32 v[38:39], v[38:39], s[2:3], v[48:49] op_sel_hi:[1,0,1]
	v_pk_fma_f32 v[36:37], v[36:37], s[2:3], v[46:47] op_sel_hi:[1,0,1]
	s_waitcnt vmcnt(6)
	v_pk_add_f32 v[38:39], v[38:39], v[52:53]
	v_pk_add_f32 v[36:37], v[36:37], v[50:51]
	s_waitcnt vmcnt(5)
	v_pk_add_f32 v[38:39], v[38:39], v[56:57]
	v_pk_add_f32 v[36:37], v[36:37], v[54:55]
	s_waitcnt vmcnt(4)
	v_pk_add_f32 v[38:39], v[38:39], v[116:117]
	v_pk_add_f32 v[36:37], v[36:37], v[114:115]
	s_waitcnt vmcnt(3)
	v_pk_add_f32 v[38:39], v[38:39], v[130:131]
	v_pk_add_f32 v[36:37], v[36:37], v[128:129]
	s_waitcnt vmcnt(2)
	v_pk_add_f32 v[38:39], v[38:39], v[134:135]
	v_pk_add_f32 v[36:37], v[36:37], v[132:133]
	s_waitcnt vmcnt(1)
	v_pk_add_f32 v[38:39], v[38:39], v[138:139]
	v_pk_add_f32 v[36:37], v[36:37], v[136:137]
	s_waitcnt vmcnt(0)
	v_pk_add_f32 v[38:39], v[38:39], v[142:143]
	v_pk_add_f32 v[36:37], v[36:37], v[140:141]

; __device__ __forceinline__ void ln_load_row(const Params& p, const float* src, int which, int r, int lane, f32x4 (&x)[8]) {
;     ...
;     const int wg = gid * 64 + k * gsz + (pm - fm), off = wg % 36, xcd = wg / 36;
;     if (off >= 32) {
;       const int j = (off - 32) * 8 + xcd;
;       f32x4 v = *(const f32x4*)(rs + 256 * k + 4 * lane) * ALPHA;
;       const float* pp = part + (size_t)j * 8 * 65536 + (r & 255) * 256 + 4 * lane;
;       f32x4 t[8];
; #pragma unroll
;       for (int q = 0; q < 8; ++q) t[q] = *(const f32x4*)(pp + (size_t)q * 65536);
; #pragma unroll
;       for (int q = 0; q < 8; ++q) v += t[q];
;       x[k] = v;
.LBB0_1509:
	s_andn2_saveexec_b64 s[36:37], s[36:37]
	s_cbranch_execz .LBB0_1511
	s_waitcnt vmcnt(0)
	v_lshlrev_b32_e32 v44, 3, v50
	s_movk_i32 s29, 0xff00
	v_add3_u32 v50, v49, v44, s29
	v_ashrrev_i32_e32 v51, 31, v50
	v_add_co_u32_e32 v44, vcc, 0x109000, v110
	v_lshlrev_b64 v[50:51], 21, v[50:51]
	s_nop 0
	v_addc_co_u32_e32 v45, vcc, 0, v111, vcc
	v_lshl_add_u64 v[58:59], v[112:113], 0, v[50:51]
	v_add_co_u32_e32 v54, vcc, 0x40000, v58
	global_load_dwordx4 v[44:47], v[44:45], off offset:3072
	s_nop 0
	v_addc_co_u32_e32 v55, vcc, 0, v59, vcc
	v_add_co_u32_e32 v62, vcc, 0x80000, v58
	global_load_dwordx4 v[50:53], v[58:59], off
	s_nop 0
	global_load_dwordx4 v[54:57], v[54:55], off
	v_addc_co_u32_e32 v63, vcc, 0, v59, vcc
	v_add_co_u32_e32 v118, vcc, 0xc0000, v58
	s_nop 1
	v_addc_co_u32_e32 v119, vcc, 0, v59, vcc
	global_load_dwordx4 v[114:117], v[62:63], off
	global_load_dwordx4 v[128:131], v[118:119], off
	v_add_co_u32_e32 v62, vcc, 0x100000, v58
	s_nop 0
	s_nop 1
	v_addc_co_u32_e32 v63, vcc, 0, v59, vcc
	v_add_co_u32_e32 v118, vcc, 0x140000, v58
	s_nop 0
	s_nop 1
	v_addc_co_u32_e32 v119, vcc, 0, v59, vcc
	global_load_dwordx4 v[132:135], v[62:63], off
	global_load_dwordx4 v[136:139], v[118:119], off
	v_add_co_u32_e32 v62, vcc, 0x180000, v58
	s_nop 0
	s_nop 1
	v_addc_co_u32_e32 v63, vcc, 0, v59, vcc
	v_add_co_u32_e32 v58, vcc, 0x1c0000, v58
	global_load_dwordx4 v[140:143], v[62:63], off
	s_nop 0
	v_addc_co_u32_e32 v59, vcc, 0, v59, vcc
	global_load_dwordx4 v[144:147], v[58:59], off
	s_waitcnt vmcnt(7)
	v_pk_fma_f32 v[46:47], v[46:47], s[2:3], v[52:53] op_sel_hi:[1,0,1]
	v_pk_fma_f32 v[44:45], v[44:45], s[2:3], v[50:51] op_sel_hi:[1,0,1]
	s_waitcnt vmcnt(6)
	v_pk_add_f32 v[46:47], v[46:47], v[56:57]
	v_pk_add_f32 v[44:45], v[44:45], v[54:55]
	s_waitcnt vmcnt(5)
	v_pk_add_f32 v[46:47], v[46:47], v[116:117]
	v_pk_add_f32 v[44:45], v[44:45], v[114:115]
	s_waitcnt vmcnt(4)
	v_pk_add_f32 v[46:47], v[46:47], v[130:131]
	v_pk_add_f32 v[44:45], v[44:45], v[128:129]
	s_waitcnt vmcnt(3)
	v_pk_add_f32 v[46:47], v[46:47], v[134:135]
	v_pk_add_f32 v[44:45], v[44:45], v[132:133]
	s_waitcnt vmcnt(2)
	v_pk_add_f32 v[46:47], v[46:47], v[138:139]
	v_pk_add_f32 v[44:45], v[44:45], v[136:137]
	s_waitcnt vmcnt(1)
	v_pk_add_f32 v[46:47], v[46:47], v[142:143]
	v_pk_add_f32 v[44:45], v[44:45], v[140:141]
	s_waitcnt vmcnt(0)
	v_pk_add_f32 v[46:47], v[46:47], v[146:147]
	v_pk_add_f32 v[44:45], v[44:45], v[144:145]

; __device__ __forceinline__ void ln_load_row(const Params& p, const float* src, int which, int r, int lane, f32x4 (&x)[8]) {
;     ...
;     const int wg = gid * 64 + k * gsz + (pm - fm), off = wg % 36, xcd = wg / 36;
;     if (off >= 32) {
;       const int j = (off - 32) * 8 + xcd;
;       f32x4 v = *(const f32x4*)(rs + 256 * k + 4 * lane) * ALPHA;
;       const float* pp = part + (size_t)j * 8 * 65536 + (r & 255) * 256 + 4 * lane;
;       f32x4 t[8];
; #pragma unroll
;       for (int q = 0; q < 8; ++q) t[q] = *(const f32x4*)(pp + (size_t)q * 65536);
; #pragma unroll
;       for (int q = 0; q < 8; ++q) v += t[q];
;       x[k] = v;
.LBB0_1513:
	s_andn2_saveexec_b64 s[36:37], s[36:37]
	s_cbranch_execz .LBB0_1515
	s_waitcnt vmcnt(0)
	v_lshlrev_b32_e32 v48, 3, v54
	s_movk_i32 s29, 0xff00
	v_add3_u32 v54, v53, v48, s29
	v_ashrrev_i32_e32 v55, 31, v54
	v_add_co_u32_e32 v48, vcc, 0x10a000, v110
	v_lshlrev_b64 v[54:55], 21, v[54:55]
	s_nop 0
	v_addc_co_u32_e32 v49, vcc, 0, v111, vcc
	v_lshl_add_u64 v[58:59], v[112:113], 0, v[54:55]
	v_add_co_u32_e32 v62, vcc, 0x40000, v58
	global_load_dwordx4 v[48:51], v[48:49], off
	s_nop 0
	v_addc_co_u32_e32 v63, vcc, 0, v59, vcc
	global_load_dwordx4 v[54:57], v[58:59], off
	global_load_dwordx4 v[114:117], v[62:63], off
	v_add_co_u32_e32 v62, vcc, 0x80000, v58
	s_nop 1
	v_addc_co_u32_e32 v63, vcc, 0, v59, vcc
	v_add_co_u32_e32 v118, vcc, 0xc0000, v58
	s_nop 0
	s_nop 1
	v_addc_co_u32_e32 v119, vcc, 0, v59, vcc
	global_load_dwordx4 v[128:131], v[62:63], off
	global_load_dwordx4 v[132:135], v[118:119], off
	v_add_co_u32_e32 v62, vcc, 0x100000, v58
	s_nop 0
	s_nop 1
	v_addc_co_u32_e32 v63, vcc, 0, v59, vcc
	v_add_co_u32_e32 v118, vcc, 0x140000, v58
	s_nop 0
	s_nop 1
	v_addc_co_u32_e32 v119, vcc, 0, v59, vcc
	global_load_dwordx4 v[136:139], v[62:63], off
	global_load_dwordx4 v[140:143], v[118:119], off
	v_add_co_u32_e32 v62, vcc, 0x180000, v58
	s_nop 1
	v_addc_co_u32_e32 v63, vcc, 0, v59, vcc
	v_add_co_u32_e32 v58, vcc, 0x1c0000, v58
	global_load_dwordx4 v[144:147], v[62:63], off
	s_nop 0
	v_addc_co_u32_e32 v59, vcc, 0, v59, vcc
	global_load_dwordx4 v[148:151], v[58:59], off
	s_waitcnt vmcnt(7)
	v_pk_fma_f32 v[50:51], v[50:51], s[2:3], v[56:57] op_sel_hi:[1,0,1]
	v_pk_fma_f32 v[48:49], v[48:49], s[2:3], v[54:55] op_sel_hi:[1,0,1]
	s_waitcnt vmcnt(6)
	v_pk_add_f32 v[50:51], v[50:51], v[116:117]
	v_pk_add_f32 v[48:49], v[48:49], v[114:115]
	s_waitcnt vmcnt(5)
	v_pk_add_f32 v[50:51], v[50:51], v[130:131]
	v_pk_add_f32 v[48:49], v[48:49], v[128:129]
	s_waitcnt vmcnt(4)
	v_pk_add_f32 v[50:51], v[50:51], v[134:135]
	v_pk_add_f32 v[48:49], v[48:49], v[132:133]
	s_waitcnt vmcnt(3)
	v_pk_add_f32 v[50:51], v[50:51], v[138:139]
	v_pk_add_f32 v[48:49], v[48:49], v[136:137]
	s_waitcnt vmcnt(2)
	v_pk_add_f32 v[50:51], v[50:51], v[142:143]
	v_pk_add_f32 v[48:49], v[48:49], v[140:141]
	s_waitcnt vmcnt(1)
	v_pk_add_f32 v[50:51], v[50:51], v[146:147]
	v_pk_add_f32 v[48:49], v[48:49], v[144:145]
	s_waitcnt vmcnt(0)
	v_pk_add_f32 v[50:51], v[50:51], v[150:151]
	v_pk_add_f32 v[48:49], v[48:49], v[148:149]

; __device__ __forceinline__ void ln_load_row(const Params& p, const float* src, int which, int r, int lane, f32x4 (&x)[8]) {
;     ...
;     const int wg = gid * 64 + k * gsz + (pm - fm), off = wg % 36, xcd = wg / 36;
;     if (off >= 32) {
;       const int j = (off - 32) * 8 + xcd;
;       f32x4 v = *(const f32x4*)(rs + 256 * k + 4 * lane) * ALPHA;
;       const float* pp = part + (size_t)j * 8 * 65536 + (r & 255) * 256 + 4 * lane;
;       f32x4 t[8];
; #pragma unroll
;       for (int q = 0; q < 8; ++q) t[q] = *(const f32x4*)(pp + (size_t)q * 65536);
; #pragma unroll
;       for (int q = 0; q < 8; ++q) v += t[q];
;       x[k] = v;
.LBB0_1517:
	s_andn2_saveexec_b64 s[36:37], s[36:37]
	s_cbranch_execz .LBB0_1519
	s_waitcnt vmcnt(0)
	v_lshlrev_b32_e32 v52, 3, v58
	s_movk_i32 s29, 0xff00
	v_add3_u32 v58, v57, v52, s29
	v_ashrrev_i32_e32 v59, 31, v58
	v_add_co_u32_e32 v52, vcc, 0x10a000, v110
	v_lshlrev_b64 v[58:59], 21, v[58:59]
	s_nop 0
	v_addc_co_u32_e32 v53, vcc, 0, v111, vcc
	v_lshl_add_u64 v[58:59], v[112:113], 0, v[58:59]
	v_add_co_u32_e32 v62, vcc, 0x40000, v58
	global_load_dwordx4 v[52:55], v[52:53], off offset:1024
	s_nop 0
	v_addc_co_u32_e32 v63, vcc, 0, v59, vcc
	global_load_dwordx4 v[114:117], v[58:59], off
	global_load_dwordx4 v[128:131], v[62:63], off
	v_add_co_u32_e32 v62, vcc, 0x80000, v58
	s_nop 1
	v_addc_co_u32_e32 v63, vcc, 0, v59, vcc
	v_add_co_u32_e32 v118, vcc, 0xc0000, v58
	s_nop 0
	s_nop 1
	v_addc_co_u32_e32 v119, vcc, 0, v59, vcc
	global_load_dwordx4 v[132:135], v[62:63], off
	global_load_dwordx4 v[136:139], v[118:119], off
	v_add_co_u32_e32 v62, vcc, 0x100000, v58
	s_nop 0
	s_nop 1
	v_addc_co_u32_e32 v63, vcc, 0, v59, vcc
	v_add_co_u32_e32 v118, vcc, 0x140000, v58
	s_nop 0
	s_nop 1
	v_addc_co_u32_e32 v119, vcc, 0, v59, vcc
	global_load_dwordx4 v[140:143], v[62:63], off
	global_load_dwordx4 v[144:147], v[118:119], off
	v_add_co_u32_e32 v62, vcc, 0x180000, v58
	s_nop 1
	v_addc_co_u32_e32 v63, vcc, 0, v59, vcc
	v_add_co_u32_e32 v58, vcc, 0x1c0000, v58
	global_load_dwordx4 v[148:151], v[62:63], off
	s_nop 0
	v_addc_co_u32_e32 v59, vcc, 0, v59, vcc
	global_load_dwordx4 v[152:155], v[58:59], off
	s_waitcnt vmcnt(7)
	v_pk_fma_f32 v[54:55], v[54:55], s[2:3], v[116:117] op_sel_hi:[1,0,1]
	v_pk_fma_f32 v[52:53], v[52:53], s[2:3], v[114:115] op_sel_hi:[1,0,1]
	s_waitcnt vmcnt(6)
	v_pk_add_f32 v[54:55], v[54:55], v[130:131]
	v_pk_add_f32 v[52:53], v[52:53], v[128:129]
	s_waitcnt vmcnt(5)
	v_pk_add_f32 v[54:55], v[54:55], v[134:135]
	v_pk_add_f32 v[52:53], v[52:53], v[132:133]
	s_waitcnt vmcnt(4)
	v_pk_add_f32 v[54:55], v[54:55], v[138:139]
	v_pk_add_f32 v[52:53], v[52:53], v[136:137]
	s_waitcnt vmcnt(3)
	v_pk_add_f32 v[54:55], v[54:55], v[142:143]
	v_pk_add_f32 v[52:53], v[52:53], v[140:141]
	s_waitcnt vmcnt(2)
	v_pk_add_f32 v[54:55], v[54:55], v[146:147]
	v_pk_add_f32 v[52:53], v[52:53], v[144:145]
	s_waitcnt vmcnt(1)
	v_pk_add_f32 v[54:55], v[54:55], v[150:151]
	v_pk_add_f32 v[52:53], v[52:53], v[148:149]
	s_waitcnt vmcnt(0)
	v_pk_add_f32 v[54:55], v[54:55], v[154:155]
	v_pk_add_f32 v[52:53], v[52:53], v[152:153]

; __device__ __forceinline__ void ln_load_row(const Params& p, const float* src, int which, int r, int lane, f32x4 (&x)[8]) {
;     ...
;     const int wg = gid * 64 + k * gsz + (pm - fm), off = wg % 36, xcd = wg / 36;
;     if (off >= 32) {
;       const int j = (off - 32) * 8 + xcd;
;       f32x4 v = *(const f32x4*)(rs + 256 * k + 4 * lane) * ALPHA;
;       const float* pp = part + (size_t)j * 8 * 65536 + (r & 255) * 256 + 4 * lane;
;       f32x4 t[8];
; #pragma unroll
;       for (int q = 0; q < 8; ++q) t[q] = *(const f32x4*)(pp + (size_t)q * 65536);
; #pragma unroll
;       for (int q = 0; q < 8; ++q) v += t[q];
;       x[k] = v;
.LBB0_1521:
	s_andn2_saveexec_b64 s[36:37], s[36:37]
	s_cbranch_execz .LBB0_1523
	s_waitcnt vmcnt(0)
	v_lshlrev_b32_e32 v56, 3, v63
	s_movk_i32 s29, 0xff00
	v_add3_u32 v62, v62, v56, s29
	v_ashrrev_i32_e32 v63, 31, v62
	v_add_co_u32_e32 v56, vcc, 0x10a000, v110
	v_lshlrev_b64 v[62:63], 21, v[62:63]
	s_nop 0
	v_addc_co_u32_e32 v57, vcc, 0, v111, vcc
	v_lshl_add_u64 v[62:63], v[112:113], 0, v[62:63]
	v_add_co_u32_e32 v118, vcc, 0x40000, v62
	global_load_dwordx4 v[56:59], v[56:57], off offset:2048
	s_nop 0
	v_addc_co_u32_e32 v119, vcc, 0, v63, vcc
	global_load_dwordx4 v[114:117], v[62:63], off
	global_load_dwordx4 v[128:131], v[118:119], off
	v_add_co_u32_e32 v118, vcc, 0x80000, v62
	s_nop 1
	v_addc_co_u32_e32 v119, vcc, 0, v63, vcc
	v_add_co_u32_e32 v136, vcc, 0xc0000, v62
	s_nop 0
	s_nop 1
	v_addc_co_u32_e32 v137, vcc, 0, v63, vcc
	global_load_dwordx4 v[132:135], v[118:119], off
	s_nop 0
	global_load_dwordx4 v[136:139], v[136:137], off
	v_add_co_u32_e32 v118, vcc, 0x100000, v62
	s_nop 0
	s_nop 1
	v_addc_co_u32_e32 v119, vcc, 0, v63, vcc
	v_add_co_u32_e32 v144, vcc, 0x140000, v62
	s_nop 0
	s_nop 1
	v_addc_co_u32_e32 v145, vcc, 0, v63, vcc
	global_load_dwordx4 v[140:143], v[118:119], off
	s_nop 0
	global_load_dwordx4 v[144:147], v[144:145], off
	v_add_co_u32_e32 v118, vcc, 0x180000, v62
	s_nop 1
	v_addc_co_u32_e32 v119, vcc, 0, v63, vcc
	v_add_co_u32_e32 v62, vcc, 0x1c0000, v62
	global_load_dwordx4 v[148:151], v[118:119], off
	s_nop 0
	v_addc_co_u32_e32 v63, vcc, 0, v63, vcc
	global_load_dwordx4 v[152:155], v[62:63], off
	s_waitcnt vmcnt(7)
	v_pk_fma_f32 v[58:59], v[58:59], s[2:3], v[116:117] op_sel_hi:[1,0,1]
	v_pk_fma_f32 v[56:57], v[56:57], s[2:3], v[114:115] op_sel_hi:[1,0,1]
	s_waitcnt vmcnt(6)
	v_pk_add_f32 v[58:59], v[58:59], v[130:131]
	v_pk_add_f32 v[56:57], v[56:57], v[128:129]
	s_waitcnt vmcnt(5)
	v_pk_add_f32 v[58:59], v[58:59], v[134:135]
	v_pk_add_f32 v[56:57], v[56:57], v[132:133]
	s_waitcnt vmcnt(4)
	v_pk_add_f32 v[58:59], v[58:59], v[138:139]
	v_pk_add_f32 v[56:57], v[56:57], v[136:137]
	s_waitcnt vmcnt(3)
	v_pk_add_f32 v[58:59], v[58:59], v[142:143]
	v_pk_add_f32 v[56:57], v[56:57], v[140:141]
	s_waitcnt vmcnt(2)
	v_pk_add_f32 v[58:59], v[58:59], v[146:147]
	v_pk_add_f32 v[56:57], v[56:57], v[144:145]
	s_waitcnt vmcnt(1)
	v_pk_add_f32 v[58:59], v[58:59], v[150:151]
	v_pk_add_f32 v[56:57], v[56:57], v[148:149]
	s_waitcnt vmcnt(0)
	v_pk_add_f32 v[58:59], v[58:59], v[154:155]
	v_pk_add_f32 v[56:57], v[56:57], v[152:153]

; __device__ __forceinline__ void ln_load_row(const Params& p, const float* src, int which, int r, int lane, f32x4 (&x)[8]) {
;     ...
;     const int wg = gid * 64 + k * gsz + (pm - fm), off = wg % 36, xcd = wg / 36;
;     if (off >= 32) {
;       const int j = (off - 32) * 8 + xcd;
;       f32x4 v = *(const f32x4*)(rs + 256 * k + 4 * lane) * ALPHA;
;       const float* pp = part + (size_t)j * 8 * 65536 + (r & 255) * 256 + 4 * lane;
;       f32x4 t[8];
; #pragma unroll
;       for (int q = 0; q < 8; ++q) t[q] = *(const f32x4*)(pp + (size_t)q * 65536);
; #pragma unroll
;       for (int q = 0; q < 8; ++q) v += t[q];
;       x[k] = v;
.LBB0_1525:
	s_andn2_saveexec_b64 s[36:37], s[36:37]
	s_cbranch_execz .LBB0_1527
	s_waitcnt vmcnt(0)
	v_lshlrev_b32_e32 v60, 3, v67
	s_movk_i32 s29, 0xff00
	v_add3_u32 v114, v64, v60, s29
	v_add_co_u32_e32 v60, vcc, 0x10a000, v110
	v_ashrrev_i32_e32 v115, 31, v114
	s_nop 0
	v_addc_co_u32_e32 v61, vcc, 0, v111, vcc
	v_lshlrev_b64 v[110:111], 21, v[114:115]
	v_lshl_add_u64 v[118:119], v[112:113], 0, v[110:111]
	v_add_co_u32_e32 v114, vcc, 0x40000, v118
	global_load_dwordx4 v[60:63], v[60:61], off offset:3072
	s_nop 0
	v_addc_co_u32_e32 v115, vcc, 0, v119, vcc
	v_add_co_u32_e32 v128, vcc, 0x80000, v118
	global_load_dwordx4 v[110:113], v[118:119], off
	s_nop 0
	global_load_dwordx4 v[114:117], v[114:115], off
	v_addc_co_u32_e32 v129, vcc, 0, v119, vcc
	v_add_co_u32_e32 v132, vcc, 0xc0000, v118
	s_nop 1
	v_addc_co_u32_e32 v133, vcc, 0, v119, vcc
	v_add_co_u32_e32 v136, vcc, 0x100000, v118
	global_load_dwordx4 v[128:131], v[128:129], off
	s_nop 0
	global_load_dwordx4 v[132:135], v[132:133], off
	v_addc_co_u32_e32 v137, vcc, 0, v119, vcc
	v_add_co_u32_e32 v140, vcc, 0x140000, v118
	s_nop 0
	s_nop 1
	v_addc_co_u32_e32 v141, vcc, 0, v119, vcc
	v_add_co_u32_e32 v144, vcc, 0x180000, v118
	global_load_dwordx4 v[136:139], v[136:137], off
	s_nop 0
	global_load_dwordx4 v[140:143], v[140:141], off
	v_addc_co_u32_e32 v145, vcc, 0, v119, vcc
	v_add_co_u32_e32 v118, vcc, 0x1c0000, v118
	global_load_dwordx4 v[144:147], v[144:145], off
	s_nop 0
	v_addc_co_u32_e32 v119, vcc, 0, v119, vcc
	global_load_dwordx4 v[148:151], v[118:119], off
	s_waitcnt vmcnt(7)
	v_pk_fma_f32 v[62:63], v[62:63], s[2:3], v[112:113] op_sel_hi:[1,0,1]
	v_pk_fma_f32 v[60:61], v[60:61], s[2:3], v[110:111] op_sel_hi:[1,0,1]
	s_waitcnt vmcnt(6)
	v_pk_add_f32 v[62:63], v[62:63], v[116:117]
	v_pk_add_f32 v[60:61], v[60:61], v[114:115]
	s_waitcnt vmcnt(5)
	v_pk_add_f32 v[62:63], v[62:63], v[130:131]
	v_pk_add_f32 v[60:61], v[60:61], v[128:129]
	s_waitcnt vmcnt(4)
	v_pk_add_f32 v[62:63], v[62:63], v[134:135]
	v_pk_add_f32 v[60:61], v[60:61], v[132:133]
	s_waitcnt vmcnt(3)
	v_pk_add_f32 v[62:63], v[62:63], v[138:139]
	v_pk_add_f32 v[60:61], v[60:61], v[136:137]
	s_waitcnt vmcnt(2)
	v_pk_add_f32 v[62:63], v[62:63], v[142:143]
	v_pk_add_f32 v[60:61], v[60:61], v[140:141]
	s_waitcnt vmcnt(1)
	v_pk_add_f32 v[62:63], v[62:63], v[146:147]
	v_pk_add_f32 v[60:61], v[60:61], v[144:145]
	s_waitcnt vmcnt(0)
	v_pk_add_f32 v[62:63], v[62:63], v[150:151]
	v_pk_add_f32 v[60:61], v[60:61], v[148:149]

; __device__ __forceinline__ void ln_load_row(const Params& p, const float* src, int which, int r, int lane, f32x4 (&x)[8]) {
;   const float* part = (const float*)(p.ws + WS_PART);
;   const float* s = src + (size_t)r * 2048;
;   const float* rs = which == 0 ? (r < TOKP ? p.in[0] + (size_t)r * 2048 : p.in[1] + (size_t)(r - TOKP) * 2048) : (const float*)(p.ws + WS_X1) + (size_t)r * 2048;
;   const int pm = r >> 8, gid = pm >> 3, fm = gid * 8, gsz = (36 - fm) < 8 ? (36 - fm) : 8;
; #pragma unroll
;   for (int k = 0; k < 8; ++k) {
;     const int wg = gid * 64 + k * gsz + (pm - fm), off = wg % 36, xcd = wg / 36;
;     if (off >= 32) {
;       const int j = (off - 32) * 8 + xcd;
;       f32x4 v = *(const f32x4*)(rs + 256 * k + 4 * lane) * ALPHA;
;       const float* pp = part + (size_t)j * 8 * 65536 + (r & 255) * 256 + 4 * lane;
;       f32x4 t[8];
; #pragma unroll
;       for (int q = 0; q < 8; ++q) t[q] = *(const f32x4*)(pp + (size_t)q * 65536);
; #pragma unroll
;       for (int q = 0; q < 8; ++q) v += t[q];
;       x[k] = v;
.LBB0_1530:
	s_or_saveexec_b64 s[44:45], s[44:45]
	v_readlane_b32 s29, v255, 10
	v_lshl_add_u64 v[114:115], v[90:91], 0, v[4:5]
	s_nop 0
	v_add_u32_e32 v4, s29, v126
	v_and_b32_e32 v4, 0xff00, v4
	v_lshlrev_b32_e32 v64, 2, v4
	v_lshl_add_u64 v[116:117], v[92:93], 0, v[64:65]
	s_xor_b64 exec, exec, s[44:45]
	s_cbranch_execz .LBB0_1532
	s_waitcnt vmcnt(0)
	v_lshlrev_b32_e32 v0, 3, v9
	s_movk_i32 s29, 0xff00
	v_add3_u32 v4, v8, v0, s29
	v_ashrrev_i32_e32 v5, 31, v4
	v_lshlrev_b64 v[4:5], 21, v[4:5]
	v_lshl_add_u64 v[4:5], v[116:117], 0, v[4:5]
	v_add_co_u32_e32 v12, vcc, 0x40000, v4
	global_load_dwordx4 v[0:3], v[114:115], off
	s_nop 0
	v_addc_co_u32_e32 v13, vcc, 0, v5, vcc
	v_add_co_u32_e32 v16, vcc, 0x80000, v4
	global_load_dwordx4 v[8:11], v[4:5], off
	s_nop 0
	global_load_dwordx4 v[12:15], v[12:13], off
	v_addc_co_u32_e32 v17, vcc, 0, v5, vcc
	v_add_co_u32_e32 v24, vcc, 0xc0000, v4
	s_nop 1
	v_addc_co_u32_e32 v25, vcc, 0, v5, vcc
	v_add_co_u32_e32 v32, vcc, 0x100000, v4
	global_load_dwordx4 v[16:19], v[16:17], off
	s_nop 0
	global_load_dwordx4 v[24:27], v[24:25], off
	v_addc_co_u32_e32 v33, vcc, 0, v5, vcc
	v_add_co_u32_e32 v40, vcc, 0x140000, v4
	s_nop 0
	s_nop 1
	v_addc_co_u32_e32 v41, vcc, 0, v5, vcc
	v_add_co_u32_e32 v118, vcc, 0x180000, v4
	global_load_dwordx4 v[32:35], v[32:33], off
	s_nop 0
	global_load_dwordx4 v[40:43], v[40:41], off
	v_addc_co_u32_e32 v119, vcc, 0, v5, vcc
	v_add_co_u32_e32 v4, vcc, 0x1c0000, v4
	global_load_dwordx4 v[128:131], v[118:119], off
	s_nop 0
	v_addc_co_u32_e32 v5, vcc, 0, v5, vcc
	global_load_dwordx4 v[132:135], v[4:5], off
	s_waitcnt vmcnt(7)
	v_pk_fma_f32 v[2:3], v[2:3], s[2:3], v[10:11] op_sel_hi:[1,0,1]
	v_pk_fma_f32 v[0:1], v[0:1], s[2:3], v[8:9] op_sel_hi:[1,0,1]
	s_waitcnt vmcnt(6)
	v_pk_add_f32 v[2:3], v[2:3], v[14:15]
	v_pk_add_f32 v[0:1], v[0:1], v[12:13]
	s_waitcnt vmcnt(5)
	v_pk_add_f32 v[2:3], v[2:3], v[18:19]
	v_pk_add_f32 v[0:1], v[0:1], v[16:17]
	s_waitcnt vmcnt(4)
	v_pk_add_f32 v[2:3], v[2:3], v[26:27]
	v_pk_add_f32 v[0:1], v[0:1], v[24:25]
	s_waitcnt vmcnt(3)
	v_pk_add_f32 v[2:3], v[2:3], v[34:35]
	v_pk_add_f32 v[0:1], v[0:1], v[32:33]
	s_waitcnt vmcnt(2)
	v_pk_add_f32 v[2:3], v[2:3], v[42:43]
	v_pk_add_f32 v[0:1], v[0:1], v[40:41]
	s_waitcnt vmcnt(1)
	v_pk_add_f32 v[2:3], v[2:3], v[130:131]
	v_pk_add_f32 v[0:1], v[0:1], v[128:129]
	s_waitcnt vmcnt(0)
	v_pk_add_f32 v[2:3], v[2:3], v[134:135]
	v_pk_add_f32 v[0:1], v[0:1], v[132:133]

; __device__ __forceinline__ void ln_load_row(const Params& p, const float* src, int which, int r, int lane, f32x4 (&x)[8]) {
;     ...
;     const int wg = gid * 64 + k * gsz + (pm - fm), off = wg % 36, xcd = wg / 36;
;     if (off >= 32) {
;       const int j = (off - 32) * 8 + xcd;
;       f32x4 v = *(const f32x4*)(rs + 256 * k + 4 * lane) * ALPHA;
;       const float* pp = part + (size_t)j * 8 * 65536 + (r & 255) * 256 + 4 * lane;
;       f32x4 t[8];
; #pragma unroll
;       for (int q = 0; q < 8; ++q) t[q] = *(const f32x4*)(pp + (size_t)q * 65536);
; #pragma unroll
;       for (int q = 0; q < 8; ++q) v += t[q];
;       x[k] = v;
.LBB0_1534:
	s_andn2_saveexec_b64 s[44:45], s[44:45]
	s_cbranch_execz .LBB0_1536
	s_waitcnt vmcnt(0)
	v_lshlrev_b32_e32 v4, 3, v10
	s_movk_i32 s29, 0xff00
	v_add3_u32 v10, v9, v4, s29
	v_ashrrev_i32_e32 v11, 31, v10
	v_lshlrev_b64 v[10:11], 21, v[10:11]
	v_lshl_add_u64 v[18:19], v[116:117], 0, v[10:11]
	v_add_co_u32_e32 v14, vcc, 0x40000, v18
	global_load_dwordx4 v[4:7], v[114:115], off offset:1024
	s_nop 0
	v_addc_co_u32_e32 v15, vcc, 0, v19, vcc
	v_add_co_u32_e32 v24, vcc, 0x80000, v18
	global_load_dwordx4 v[10:13], v[18:19], off
	s_nop 0
	global_load_dwordx4 v[14:17], v[14:15], off
	v_addc_co_u32_e32 v25, vcc, 0, v19, vcc
	v_add_co_u32_e32 v32, vcc, 0xc0000, v18
	s_nop 1
	v_addc_co_u32_e32 v33, vcc, 0, v19, vcc
	v_add_co_u32_e32 v42, vcc, 0x100000, v18
	global_load_dwordx4 v[24:27], v[24:25], off
	s_nop 0
	global_load_dwordx4 v[32:35], v[32:33], off
	v_addc_co_u32_e32 v43, vcc, 0, v19, vcc
	v_add_co_u32_e32 v118, vcc, 0x140000, v18
	s_nop 0
	s_nop 1
	v_addc_co_u32_e32 v119, vcc, 0, v19, vcc
	global_load_dwordx4 v[128:131], v[42:43], off
	global_load_dwordx4 v[132:135], v[118:119], off
	v_add_co_u32_e32 v42, vcc, 0x180000, v18
	s_nop 0
	s_nop 1
	v_addc_co_u32_e32 v43, vcc, 0, v19, vcc
	v_add_co_u32_e32 v18, vcc, 0x1c0000, v18
	global_load_dwordx4 v[136:139], v[42:43], off
	s_nop 0
	v_addc_co_u32_e32 v19, vcc, 0, v19, vcc
	global_load_dwordx4 v[140:143], v[18:19], off
	s_waitcnt vmcnt(7)
	v_pk_fma_f32 v[6:7], v[6:7], s[2:3], v[12:13] op_sel_hi:[1,0,1]
	v_pk_fma_f32 v[4:5], v[4:5], s[2:3], v[10:11] op_sel_hi:[1,0,1]
	s_waitcnt vmcnt(6)
	v_pk_add_f32 v[6:7], v[6:7], v[16:17]
	v_pk_add_f32 v[4:5], v[4:5], v[14:15]
	s_waitcnt vmcnt(5)
	v_pk_add_f32 v[6:7], v[6:7], v[26:27]
	v_pk_add_f32 v[4:5], v[4:5], v[24:25]
	s_waitcnt vmcnt(4)
	v_pk_add_f32 v[6:7], v[6:7], v[34:35]
	v_pk_add_f32 v[4:5], v[4:5], v[32:33]
	s_waitcnt vmcnt(3)
	v_pk_add_f32 v[6:7], v[6:7], v[130:131]
	v_pk_add_f32 v[4:5], v[4:5], v[128:129]
	s_waitcnt vmcnt(2)
	v_pk_add_f32 v[6:7], v[6:7], v[134:135]
	v_pk_add_f32 v[4:5], v[4:5], v[132:133]
	s_waitcnt vmcnt(1)
	v_pk_add_f32 v[6:7], v[6:7], v[138:139]
	v_pk_add_f32 v[4:5], v[4:5], v[136:137]
	s_waitcnt vmcnt(0)
	v_pk_add_f32 v[6:7], v[6:7], v[142:143]
	v_pk_add_f32 v[4:5], v[4:5], v[140:141]

; __device__ __forceinline__ void ln_load_row(const Params& p, const float* src, int which, int r, int lane, f32x4 (&x)[8]) {
;     ...
;     const int wg = gid * 64 + k * gsz + (pm - fm), off = wg % 36, xcd = wg / 36;
;     if (off >= 32) {
;       const int j = (off - 32) * 8 + xcd;
;       f32x4 v = *(const f32x4*)(rs + 256 * k + 4 * lane) * ALPHA;
;       const float* pp = part + (size_t)j * 8 * 65536 + (r & 255) * 256 + 4 * lane;
;       f32x4 t[8];
; #pragma unroll
;       for (int q = 0; q < 8; ++q) t[q] = *(const f32x4*)(pp + (size_t)q * 65536);
; #pragma unroll
;       for (int q = 0; q < 8; ++q) v += t[q];
;       x[k] = v;
.LBB0_1538:
	s_andn2_saveexec_b64 s[44:45], s[44:45]
	s_cbranch_execz .LBB0_1540
	s_waitcnt vmcnt(0)
	v_lshlrev_b32_e32 v8, 3, v14
	s_movk_i32 s29, 0xff00
	v_add3_u32 v14, v13, v8, s29
	v_ashrrev_i32_e32 v15, 31, v14
	v_lshlrev_b64 v[14:15], 21, v[14:15]
	v_lshl_add_u64 v[18:19], v[116:117], 0, v[14:15]
	v_add_co_u32_e32 v24, vcc, 0x40000, v18
	global_load_dwordx4 v[8:11], v[114:115], off offset:2048
	s_nop 0
	v_addc_co_u32_e32 v25, vcc, 0, v19, vcc
	v_add_co_u32_e32 v32, vcc, 0x80000, v18
	global_load_dwordx4 v[14:17], v[18:19], off
	s_nop 0
	global_load_dwordx4 v[24:27], v[24:25], off
	v_addc_co_u32_e32 v33, vcc, 0, v19, vcc
	v_add_co_u32_e32 v42, vcc, 0xc0000, v18
	s_nop 1
	v_addc_co_u32_e32 v43, vcc, 0, v19, vcc
	global_load_dwordx4 v[32:35], v[32:33], off
	s_nop 0
	global_load_dwordx4 v[128:131], v[42:43], off
	v_add_co_u32_e32 v42, vcc, 0x100000, v18
	s_nop 0
	s_nop 1
	v_addc_co_u32_e32 v43, vcc, 0, v19, vcc
	v_add_co_u32_e32 v118, vcc, 0x140000, v18
	s_nop 0
	s_nop 1
	v_addc_co_u32_e32 v119, vcc, 0, v19, vcc
	global_load_dwordx4 v[132:135], v[42:43], off
	global_load_dwordx4 v[136:139], v[118:119], off
	v_add_co_u32_e32 v42, vcc, 0x180000, v18
	s_nop 0
	s_nop 1
	v_addc_co_u32_e32 v43, vcc, 0, v19, vcc
	v_add_co_u32_e32 v18, vcc, 0x1c0000, v18
	global_load_dwordx4 v[140:143], v[42:43], off
	s_nop 0
	v_addc_co_u32_e32 v19, vcc, 0, v19, vcc
	global_load_dwordx4 v[144:147], v[18:19], off
	s_waitcnt vmcnt(7)
	v_pk_fma_f32 v[10:11], v[10:11], s[2:3], v[16:17] op_sel_hi:[1,0,1]
	v_pk_fma_f32 v[8:9], v[8:9], s[2:3], v[14:15] op_sel_hi:[1,0,1]
	s_waitcnt vmcnt(6)
	v_pk_add_f32 v[10:11], v[10:11], v[26:27]
	v_pk_add_f32 v[8:9], v[8:9], v[24:25]
	s_waitcnt vmcnt(5)
	v_pk_add_f32 v[10:11], v[10:11], v[34:35]
	v_pk_add_f32 v[8:9], v[8:9], v[32:33]
	s_waitcnt vmcnt(4)
	v_pk_add_f32 v[10:11], v[10:11], v[130:131]
	v_pk_add_f32 v[8:9], v[8:9], v[128:129]
	s_waitcnt vmcnt(3)
	v_pk_add_f32 v[10:11], v[10:11], v[134:135]
	v_pk_add_f32 v[8:9], v[8:9], v[132:133]
	s_waitcnt vmcnt(2)
	v_pk_add_f32 v[10:11], v[10:11], v[138:139]
	v_pk_add_f32 v[8:9], v[8:9], v[136:137]
	s_waitcnt vmcnt(1)
	v_pk_add_f32 v[10:11], v[10:11], v[142:143]
	v_pk_add_f32 v[8:9], v[8:9], v[140:141]
	s_waitcnt vmcnt(0)
	v_pk_add_f32 v[10:11], v[10:11], v[146:147]
	v_pk_add_f32 v[8:9], v[8:9], v[144:145]

; __device__ __forceinline__ void ln_load_row(const Params& p, const float* src, int which, int r, int lane, f32x4 (&x)[8]) {
;     ...
;     const int wg = gid * 64 + k * gsz + (pm - fm), off = wg % 36, xcd = wg / 36;
;     if (off >= 32) {
;       const int j = (off - 32) * 8 + xcd;
;       f32x4 v = *(const f32x4*)(rs + 256 * k + 4 * lane) * ALPHA;
;       const float* pp = part + (size_t)j * 8 * 65536 + (r & 255) * 256 + 4 * lane;
;       f32x4 t[8];
; #pragma unroll
;       for (int q = 0; q < 8; ++q) t[q] = *(const f32x4*)(pp + (size_t)q * 65536);
; #pragma unroll
;       for (int q = 0; q < 8; ++q) v += t[q];
;       x[k] = v;
.LBB0_1542:
	s_andn2_saveexec_b64 s[44:45], s[44:45]
	s_cbranch_execz .LBB0_1544
	s_waitcnt vmcnt(0)
	v_lshlrev_b32_e32 v12, 3, v18
	s_movk_i32 s29, 0xff00
	v_add3_u32 v18, v17, v12, s29
	v_ashrrev_i32_e32 v19, 31, v18
	v_lshlrev_b64 v[18:19], 21, v[18:19]
	v_lshl_add_u64 v[18:19], v[116:117], 0, v[18:19]
	v_add_co_u32_e32 v32, vcc, 0x40000, v18
	global_load_dwordx4 v[12:15], v[114:115], off offset:3072
	s_nop 0
	v_addc_co_u32_e32 v33, vcc, 0, v19, vcc
	v_add_co_u32_e32 v42, vcc, 0x80000, v18
	global_load_dwordx4 v[24:27], v[18:19], off
	s_nop 0
	global_load_dwordx4 v[32:35], v[32:33], off
	v_addc_co_u32_e32 v43, vcc, 0, v19, vcc
	v_add_co_u32_e32 v118, vcc, 0xc0000, v18
	s_nop 1
	v_addc_co_u32_e32 v119, vcc, 0, v19, vcc
	global_load_dwordx4 v[128:131], v[42:43], off
	global_load_dwordx4 v[132:135], v[118:119], off
	v_add_co_u32_e32 v42, vcc, 0x100000, v18
	s_nop 0
	s_nop 1
	v_addc_co_u32_e32 v43, vcc, 0, v19, vcc
	v_add_co_u32_e32 v118, vcc, 0x140000, v18
	s_nop 0
	s_nop 1
	v_addc_co_u32_e32 v119, vcc, 0, v19, vcc
	global_load_dwordx4 v[136:139], v[42:43], off
	global_load_dwordx4 v[140:143], v[118:119], off
	v_add_co_u32_e32 v42, vcc, 0x180000, v18
	s_nop 0
	s_nop 1
	v_addc_co_u32_e32 v43, vcc, 0, v19, vcc
	v_add_co_u32_e32 v18, vcc, 0x1c0000, v18
	global_load_dwordx4 v[144:147], v[42:43], off
	s_nop 0
	v_addc_co_u32_e32 v19, vcc, 0, v19, vcc
	global_load_dwordx4 v[148:151], v[18:19], off
	s_waitcnt vmcnt(7)
	v_pk_fma_f32 v[14:15], v[14:15], s[2:3], v[26:27] op_sel_hi:[1,0,1]
	v_pk_fma_f32 v[12:13], v[12:13], s[2:3], v[24:25] op_sel_hi:[1,0,1]
	s_waitcnt vmcnt(6)
	v_pk_add_f32 v[14:15], v[14:15], v[34:35]
	v_pk_add_f32 v[12:13], v[12:13], v[32:33]
	s_waitcnt vmcnt(5)
	v_pk_add_f32 v[14:15], v[14:15], v[130:131]
	v_pk_add_f32 v[12:13], v[12:13], v[128:129]
	s_waitcnt vmcnt(4)
	v_pk_add_f32 v[14:15], v[14:15], v[134:135]
	v_pk_add_f32 v[12:13], v[12:13], v[132:133]
	s_waitcnt vmcnt(3)
	v_pk_add_f32 v[14:15], v[14:15], v[138:139]
	v_pk_add_f32 v[12:13], v[12:13], v[136:137]
	s_waitcnt vmcnt(2)
	v_pk_add_f32 v[14:15], v[14:15], v[142:143]
	v_pk_add_f32 v[12:13], v[12:13], v[140:141]
	s_waitcnt vmcnt(1)
	v_pk_add_f32 v[14:15], v[14:15], v[146:147]
	v_pk_add_f32 v[12:13], v[12:13], v[144:145]
	s_waitcnt vmcnt(0)
	v_pk_add_f32 v[14:15], v[14:15], v[150:151]
	v_pk_add_f32 v[12:13], v[12:13], v[148:149]

; __device__ __forceinline__ void ln_load_row(const Params& p, const float* src, int which, int r, int lane, f32x4 (&x)[8]) {
;     ...
;     const int wg = gid * 64 + k * gsz + (pm - fm), off = wg % 36, xcd = wg / 36;
;     if (off >= 32) {
;       const int j = (off - 32) * 8 + xcd;
;       f32x4 v = *(const f32x4*)(rs + 256 * k + 4 * lane) * ALPHA;
;       const float* pp = part + (size_t)j * 8 * 65536 + (r & 255) * 256 + 4 * lane;
;       f32x4 t[8];
; #pragma unroll
;       for (int q = 0; q < 8; ++q) t[q] = *(const f32x4*)(pp + (size_t)q * 65536);
; #pragma unroll
;       for (int q = 0; q < 8; ++q) v += t[q];
;       x[k] = v;
.LBB0_1546:
	s_andn2_saveexec_b64 s[44:45], s[44:45]
	s_cbranch_execz .LBB0_1548
	s_waitcnt vmcnt(0)
	v_lshlrev_b32_e32 v16, 3, v26
	s_movk_i32 s29, 0xff00
	v_add3_u32 v16, v25, v16, s29
	v_ashrrev_i32_e32 v17, 31, v16
	v_add_co_u32_e32 v18, vcc, 0x1000, v114
	v_lshlrev_b64 v[16:17], 21, v[16:17]
	s_nop 0
	v_addc_co_u32_e32 v19, vcc, 0, v115, vcc
	v_lshl_add_u64 v[26:27], v[116:117], 0, v[16:17]
	v_add_co_u32_e32 v42, vcc, 0x40000, v26
	global_load_dwordx4 v[16:19], v[18:19], off
	s_nop 0
	global_load_dwordx4 v[32:35], v[26:27], off
	v_addc_co_u32_e32 v43, vcc, 0, v27, vcc
	v_add_co_u32_e32 v118, vcc, 0x80000, v26
	s_nop 1
	v_addc_co_u32_e32 v119, vcc, 0, v27, vcc
	global_load_dwordx4 v[128:131], v[42:43], off
	global_load_dwordx4 v[132:135], v[118:119], off
	v_add_co_u32_e32 v42, vcc, 0xc0000, v26
	s_nop 0
	s_nop 1
	v_addc_co_u32_e32 v43, vcc, 0, v27, vcc
	v_add_co_u32_e32 v118, vcc, 0x100000, v26
	s_nop 1
	v_addc_co_u32_e32 v119, vcc, 0, v27, vcc
	global_load_dwordx4 v[136:139], v[42:43], off
	global_load_dwordx4 v[140:143], v[118:119], off
	v_add_co_u32_e32 v42, vcc, 0x140000, v26
	s_nop 0
	s_nop 1
	v_addc_co_u32_e32 v43, vcc, 0, v27, vcc
	v_add_co_u32_e32 v118, vcc, 0x180000, v26
	s_nop 0
	s_nop 1
	v_addc_co_u32_e32 v119, vcc, 0, v27, vcc
	v_add_co_u32_e32 v26, vcc, 0x1c0000, v26
	global_load_dwordx4 v[144:147], v[42:43], off
	global_load_dwordx4 v[148:151], v[118:119], off
	v_addc_co_u32_e32 v27, vcc, 0, v27, vcc
	global_load_dwordx4 v[152:155], v[26:27], off
	s_waitcnt vmcnt(7)
	v_pk_fma_f32 v[18:19], v[18:19], s[2:3], v[34:35] op_sel_hi:[1,0,1]
	v_pk_fma_f32 v[16:17], v[16:17], s[2:3], v[32:33] op_sel_hi:[1,0,1]
	s_waitcnt vmcnt(6)
	v_pk_add_f32 v[18:19], v[18:19], v[130:131]
	v_pk_add_f32 v[16:17], v[16:17], v[128:129]
	s_waitcnt vmcnt(5)
	v_pk_add_f32 v[18:19], v[18:19], v[134:135]
	v_pk_add_f32 v[16:17], v[16:17], v[132:133]
	s_waitcnt vmcnt(4)
	v_pk_add_f32 v[18:19], v[18:19], v[138:139]
	v_pk_add_f32 v[16:17], v[16:17], v[136:137]
	s_waitcnt vmcnt(3)
	v_pk_add_f32 v[18:19], v[18:19], v[142:143]
	v_pk_add_f32 v[16:17], v[16:17], v[140:141]
	s_waitcnt vmcnt(2)
	v_pk_add_f32 v[18:19], v[18:19], v[146:147]
	v_pk_add_f32 v[16:17], v[16:17], v[144:145]
	s_waitcnt vmcnt(1)
	v_pk_add_f32 v[18:19], v[18:19], v[150:151]
	v_pk_add_f32 v[16:17], v[16:17], v[148:149]
	s_waitcnt vmcnt(0)
	v_pk_add_f32 v[18:19], v[18:19], v[154:155]
	v_pk_add_f32 v[16:17], v[16:17], v[152:153]

; __device__ __forceinline__ void ln_load_row(const Params& p, const float* src, int which, int r, int lane, f32x4 (&x)[8]) {
;     ...
;     const int wg = gid * 64 + k * gsz + (pm - fm), off = wg % 36, xcd = wg / 36;
;     if (off >= 32) {
;       const int j = (off - 32) * 8 + xcd;
;       f32x4 v = *(const f32x4*)(rs + 256 * k + 4 * lane) * ALPHA;
;       const float* pp = part + (size_t)j * 8 * 65536 + (r & 255) * 256 + 4 * lane;
;       f32x4 t[8];
; #pragma unroll
;       for (int q = 0; q < 8; ++q) t[q] = *(const f32x4*)(pp + (size_t)q * 65536);
; #pragma unroll
;       for (int q = 0; q < 8; ++q) v += t[q];
;       x[k] = v;
.LBB0_1550:
	s_andn2_saveexec_b64 s[44:45], s[44:45]
	s_cbranch_execz .LBB0_1552
	s_waitcnt vmcnt(0)
	v_lshlrev_b32_e32 v24, 3, v34
	s_movk_i32 s29, 0xff00
	v_add3_u32 v24, v33, v24, s29
	v_ashrrev_i32_e32 v25, 31, v24
	v_add_co_u32_e32 v26, vcc, 0x1000, v114
	v_lshlrev_b64 v[24:25], 21, v[24:25]
	s_nop 0
	v_addc_co_u32_e32 v27, vcc, 0, v115, vcc
	v_lshl_add_u64 v[34:35], v[116:117], 0, v[24:25]
	v_add_co_u32_e32 v42, vcc, 0x40000, v34
	global_load_dwordx4 v[24:27], v[26:27], off offset:1024
	s_nop 0
	global_load_dwordx4 v[128:131], v[34:35], off
	v_addc_co_u32_e32 v43, vcc, 0, v35, vcc
	v_add_co_u32_e32 v118, vcc, 0x80000, v34
	s_nop 1
	v_addc_co_u32_e32 v119, vcc, 0, v35, vcc
	global_load_dwordx4 v[132:135], v[42:43], off
	global_load_dwordx4 v[136:139], v[118:119], off
	v_add_co_u32_e32 v42, vcc, 0xc0000, v34
	s_nop 0
	s_nop 1
	v_addc_co_u32_e32 v43, vcc, 0, v35, vcc
	v_add_co_u32_e32 v118, vcc, 0x100000, v34
	s_nop 1
	v_addc_co_u32_e32 v119, vcc, 0, v35, vcc
	global_load_dwordx4 v[140:143], v[42:43], off
	global_load_dwordx4 v[144:147], v[118:119], off
	v_add_co_u32_e32 v42, vcc, 0x140000, v34
	s_nop 0
	s_nop 1
	v_addc_co_u32_e32 v43, vcc, 0, v35, vcc
	v_add_co_u32_e32 v118, vcc, 0x180000, v34
	s_nop 0
	s_nop 1
	v_addc_co_u32_e32 v119, vcc, 0, v35, vcc
	v_add_co_u32_e32 v34, vcc, 0x1c0000, v34
	global_load_dwordx4 v[148:151], v[42:43], off
	global_load_dwordx4 v[152:155], v[118:119], off
	v_addc_co_u32_e32 v35, vcc, 0, v35, vcc
	global_load_dwordx4 v[156:159], v[34:35], off
	s_waitcnt vmcnt(7)
	v_pk_fma_f32 v[26:27], v[26:27], s[2:3], v[130:131] op_sel_hi:[1,0,1]
	v_pk_fma_f32 v[24:25], v[24:25], s[2:3], v[128:129] op_sel_hi:[1,0,1]
	s_waitcnt vmcnt(6)
	v_pk_add_f32 v[26:27], v[26:27], v[134:135]
	v_pk_add_f32 v[24:25], v[24:25], v[132:133]
	s_waitcnt vmcnt(5)
	v_pk_add_f32 v[26:27], v[26:27], v[138:139]
	v_pk_add_f32 v[24:25], v[24:25], v[136:137]
	s_waitcnt vmcnt(4)
	v_pk_add_f32 v[26:27], v[26:27], v[142:143]
	v_pk_add_f32 v[24:25], v[24:25], v[140:141]
	s_waitcnt vmcnt(3)
	v_pk_add_f32 v[26:27], v[26:27], v[146:147]
	v_pk_add_f32 v[24:25], v[24:25], v[144:145]
	s_waitcnt vmcnt(2)
	v_pk_add_f32 v[26:27], v[26:27], v[150:151]
	v_pk_add_f32 v[24:25], v[24:25], v[148:149]
	s_waitcnt vmcnt(1)
	v_pk_add_f32 v[26:27], v[26:27], v[154:155]
	v_pk_add_f32 v[24:25], v[24:25], v[152:153]
	s_waitcnt vmcnt(0)
	v_pk_add_f32 v[26:27], v[26:27], v[158:159]
	v_pk_add_f32 v[24:25], v[24:25], v[156:157]

; __device__ __forceinline__ void ln_load_row(const Params& p, const float* src, int which, int r, int lane, f32x4 (&x)[8]) {
;     ...
;     const int wg = gid * 64 + k * gsz + (pm - fm), off = wg % 36, xcd = wg / 36;
;     if (off >= 32) {
;       const int j = (off - 32) * 8 + xcd;
;       f32x4 v = *(const f32x4*)(rs + 256 * k + 4 * lane) * ALPHA;
;       const float* pp = part + (size_t)j * 8 * 65536 + (r & 255) * 256 + 4 * lane;
;       f32x4 t[8];
; #pragma unroll
;       for (int q = 0; q < 8; ++q) t[q] = *(const f32x4*)(pp + (size_t)q * 65536);
; #pragma unroll
;       for (int q = 0; q < 8; ++q) v += t[q];
;       x[k] = v;
.LBB0_1554:
	s_andn2_saveexec_b64 s[44:45], s[44:45]
	s_cbranch_execz .LBB0_1556
	s_waitcnt vmcnt(0)
	v_lshlrev_b32_e32 v32, 3, v43
	s_movk_i32 s29, 0xff00
	v_add3_u32 v32, v42, v32, s29
	v_ashrrev_i32_e32 v33, 31, v32
	v_add_co_u32_e32 v34, vcc, 0x1000, v114
	v_lshlrev_b64 v[32:33], 21, v[32:33]
	s_nop 0
	v_addc_co_u32_e32 v35, vcc, 0, v115, vcc
	v_lshl_add_u64 v[42:43], v[116:117], 0, v[32:33]
	v_add_co_u32_e32 v118, vcc, 0x40000, v42
	global_load_dwordx4 v[32:35], v[34:35], off offset:2048
	s_nop 0
	global_load_dwordx4 v[128:131], v[42:43], off
	v_addc_co_u32_e32 v119, vcc, 0, v43, vcc
	v_add_co_u32_e32 v136, vcc, 0x80000, v42
	s_nop 1
	v_addc_co_u32_e32 v137, vcc, 0, v43, vcc
	global_load_dwordx4 v[132:135], v[118:119], off
	s_nop 0
	global_load_dwordx4 v[136:139], v[136:137], off
	v_add_co_u32_e32 v118, vcc, 0xc0000, v42
	s_nop 0
	s_nop 1
	v_addc_co_u32_e32 v119, vcc, 0, v43, vcc
	v_add_co_u32_e32 v144, vcc, 0x100000, v42
	s_nop 1
	v_addc_co_u32_e32 v145, vcc, 0, v43, vcc
	global_load_dwordx4 v[140:143], v[118:119], off
	s_nop 0
	global_load_dwordx4 v[144:147], v[144:145], off
	v_add_co_u32_e32 v118, vcc, 0x140000, v42
	s_nop 0
	s_nop 1
	v_addc_co_u32_e32 v119, vcc, 0, v43, vcc
	v_add_co_u32_e32 v152, vcc, 0x180000, v42
	s_nop 0
	s_nop 1
	v_addc_co_u32_e32 v153, vcc, 0, v43, vcc
	v_add_co_u32_e32 v42, vcc, 0x1c0000, v42
	global_load_dwordx4 v[148:151], v[118:119], off
	s_nop 0
	global_load_dwordx4 v[152:155], v[152:153], off
	v_addc_co_u32_e32 v43, vcc, 0, v43, vcc
	global_load_dwordx4 v[156:159], v[42:43], off
	s_waitcnt vmcnt(7)
	v_pk_fma_f32 v[34:35], v[34:35], s[2:3], v[130:131] op_sel_hi:[1,0,1]
	v_pk_fma_f32 v[32:33], v[32:33], s[2:3], v[128:129] op_sel_hi:[1,0,1]
	s_waitcnt vmcnt(6)
	v_pk_add_f32 v[34:35], v[34:35], v[134:135]
	v_pk_add_f32 v[32:33], v[32:33], v[132:133]
	s_waitcnt vmcnt(5)
	v_pk_add_f32 v[34:35], v[34:35], v[138:139]
	v_pk_add_f32 v[32:33], v[32:33], v[136:137]
	s_waitcnt vmcnt(4)
	v_pk_add_f32 v[34:35], v[34:35], v[142:143]
	v_pk_add_f32 v[32:33], v[32:33], v[140:141]
	s_waitcnt vmcnt(3)
	v_pk_add_f32 v[34:35], v[34:35], v[146:147]
	v_pk_add_f32 v[32:33], v[32:33], v[144:145]
	s_waitcnt vmcnt(2)
	v_pk_add_f32 v[34:35], v[34:35], v[150:151]
	v_pk_add_f32 v[32:33], v[32:33], v[148:149]
	s_waitcnt vmcnt(1)
	v_pk_add_f32 v[34:35], v[34:35], v[154:155]
	v_pk_add_f32 v[32:33], v[32:33], v[152:153]
	s_waitcnt vmcnt(0)
	v_pk_add_f32 v[34:35], v[34:35], v[158:159]
	v_pk_add_f32 v[32:33], v[32:33], v[156:157]

; __device__ __forceinline__ void ln_load_row(const Params& p, const float* src, int which, int r, int lane, f32x4 (&x)[8]) {
;     ...
;     const int wg = gid * 64 + k * gsz + (pm - fm), off = wg % 36, xcd = wg / 36;
;     if (off >= 32) {
;       const int j = (off - 32) * 8 + xcd;
;       f32x4 v = *(const f32x4*)(rs + 256 * k + 4 * lane) * ALPHA;
;       const float* pp = part + (size_t)j * 8 * 65536 + (r & 255) * 256 + 4 * lane;
;       f32x4 t[8];
; #pragma unroll
;       for (int q = 0; q < 8; ++q) t[q] = *(const f32x4*)(pp + (size_t)q * 65536);
; #pragma unroll
;       for (int q = 0; q < 8; ++q) v += t[q];
;       x[k] = v;
.LBB0_1558:
	s_andn2_saveexec_b64 s[44:45], s[44:45]
	s_cbranch_execz .LBB0_1560
	s_waitcnt vmcnt(0)
	v_lshlrev_b32_e32 v40, 3, v67
	s_movk_i32 s29, 0xff00
	v_add3_u32 v40, v64, v40, s29
	v_ashrrev_i32_e32 v41, 31, v40
	v_add_co_u32_e32 v42, vcc, 0x1000, v114
	v_lshlrev_b64 v[40:41], 21, v[40:41]
	s_nop 0
	v_addc_co_u32_e32 v43, vcc, 0, v115, vcc
	v_lshl_add_u64 v[148:149], v[116:117], 0, v[40:41]
	v_add_co_u32_e32 v116, vcc, 0x40000, v148
	global_load_dwordx4 v[40:43], v[42:43], off offset:3072
	s_nop 0
	global_load_dwordx4 v[112:115], v[148:149], off
	v_addc_co_u32_e32 v117, vcc, 0, v149, vcc
	v_add_co_u32_e32 v128, vcc, 0x80000, v148
	s_nop 1
	v_addc_co_u32_e32 v129, vcc, 0, v149, vcc
	v_add_co_u32_e32 v132, vcc, 0xc0000, v148
	global_load_dwordx4 v[116:119], v[116:117], off
	s_nop 0
	global_load_dwordx4 v[128:131], v[128:129], off
	v_addc_co_u32_e32 v133, vcc, 0, v149, vcc
	v_add_co_u32_e32 v136, vcc, 0x100000, v148
	s_nop 0
	s_nop 1
	v_addc_co_u32_e32 v137, vcc, 0, v149, vcc
	v_add_co_u32_e32 v140, vcc, 0x140000, v148
	global_load_dwordx4 v[132:135], v[132:133], off
	s_nop 0
	global_load_dwordx4 v[136:139], v[136:137], off
	v_addc_co_u32_e32 v141, vcc, 0, v149, vcc
	v_add_co_u32_e32 v144, vcc, 0x180000, v148
	s_nop 1
	v_addc_co_u32_e32 v145, vcc, 0, v149, vcc
	v_add_co_u32_e32 v148, vcc, 0x1c0000, v148
	global_load_dwordx4 v[140:143], v[140:141], off
	s_nop 0
	global_load_dwordx4 v[144:147], v[144:145], off
	v_addc_co_u32_e32 v149, vcc, 0, v149, vcc
	global_load_dwordx4 v[148:151], v[148:149], off
	s_waitcnt vmcnt(7)
	v_pk_fma_f32 v[42:43], v[42:43], s[2:3], v[114:115] op_sel_hi:[1,0,1]
	v_pk_fma_f32 v[40:41], v[40:41], s[2:3], v[112:113] op_sel_hi:[1,0,1]
	s_waitcnt vmcnt(6)
	v_pk_add_f32 v[42:43], v[42:43], v[118:119]
	v_pk_add_f32 v[40:41], v[40:41], v[116:117]
	s_waitcnt vmcnt(5)
	v_pk_add_f32 v[42:43], v[42:43], v[130:131]
	v_pk_add_f32 v[40:41], v[40:41], v[128:129]
	s_waitcnt vmcnt(4)
	v_pk_add_f32 v[42:43], v[42:43], v[134:135]
	v_pk_add_f32 v[40:41], v[40:41], v[132:133]
	s_waitcnt vmcnt(3)
	v_pk_add_f32 v[42:43], v[42:43], v[138:139]
	v_pk_add_f32 v[40:41], v[40:41], v[136:137]
	s_waitcnt vmcnt(2)
	v_pk_add_f32 v[42:43], v[42:43], v[142:143]
	v_pk_add_f32 v[40:41], v[40:41], v[140:141]
	s_waitcnt vmcnt(1)
	v_pk_add_f32 v[42:43], v[42:43], v[146:147]
	v_pk_add_f32 v[40:41], v[40:41], v[144:145]
	s_waitcnt vmcnt(0)
	v_pk_add_f32 v[42:43], v[42:43], v[150:151]
	v_pk_add_f32 v[40:41], v[40:41], v[148:149]
